# scan split over 64 blocks (2 per sequence, 64 dv columns each): 4 compute waves + 4 helper waves computing W
# speedup vs baseline: 1.3320x; 1.0700x over previous
; __device__ __forceinline__ void phase_side(KP kp_, int bid, int nb){ asm volatile("" : "+s"(kp_)); const Params p=load_params(kp_);
;     ...
;   for (int j=bid; j<768; j+=nb){ int w=j>>8; int r=j&255; int nt_=r>>4, kt=r&15;
;     const float* src = w==0?p.w_pa:(w==1?p.w_pb:p.w_out); size_t off = w==0?OFF_WTPA:(w==1?OFF_WTPB:OFF_WTOUT);
;     transpose_tile(src,1024,1,(u16*)(ws+off),nt_*64,kt*64,tid); }
;   _Float16* a3=(_Float16*)(ws+OFF_A3);
;   for (int t=bid*8+wid; t<8192; t+=nb*8){
; __global__ void __launch_bounds__(NTH) mega(Params p_arg){
;     ...
;   if (gridDim.x>64){ if (blockIdx.x<32) phase_scan(kp); else phase_side(kp,blockIdx.x-32,gridDim.x-32); }
;   else { phase_scan(kp); phase_side(kp,blockIdx.x,gridDim.x); }
.LBB0_871:
	s_and_b64 vcc, exec, s[0:1]
	s_cbranch_vccz .LBB0_960
	s_cmp_gt_u32 s75, 63
	s_mov_b64 s[0:1], -1
	s_cbranch_scc0 .LBB0_919
	s_sub_i32 s98, s75, 32
	s_sub_i32 s99, s76, 32
	s_mov_b64 s[6:7], s[78:79]
	s_load_dwordx8 s[12:19], s[6:7], 0x70
	s_load_dwordx4 s[20:23], s[6:7], 0x90
	s_load_dwordx2 s[4:5], s[6:7], 0xa8
	s_load_dwordx2 s[0:1], s[6:7], 0xe0
	s_sub_i32 s33, s98, 32
	s_sub_i32 s34, s99, 32
	s_waitcnt vmcnt(0)
	v_mov_b32_e32 v10, v154
	s_cmpk_gt_i32 s33, 0x2ff
	s_cbranch_scc1 .LBB0_876
	v_lshlrev_b32_e32 v0, 2, v10
	v_and_b32_e32 v4, 60, v0
	v_add_u32_e32 v0, 0x200, v10
	s_load_dwordx4 s[8:11], s[6:7], 0xb8
	s_load_dwordx2 s[2:3], s[6:7], 0xc8
	v_ashrrev_i32_e32 v6, 4, v0
	v_lshlrev_b32_e32 v0, 3, v10
	v_ashrrev_i32_e32 v5, 4, v10
	s_movk_i32 s6, 0x110
	v_ashrrev_i32_e32 v7, 3, v10
	v_and_b32_e32 v0, 56, v0
	v_mul_lo_u32 v3, v5, s6
	v_mul_lo_u32 v11, v6, s6
	v_mul_u32_u24_e32 v1, 0x110, v0
	v_lshlrev_b32_e32 v8, 2, v7
	s_lshl_b32 s6, s98, 6
	v_lshl_add_u32 v2, v4, 2, 0
	v_add3_u32 v8, 0, v1, v8
	v_mov_b32_e32 v1, 0
	s_add_i32 s24, s6, 0xfffff800
	s_lshl_b32 s25, s99, 6
	s_lshl_b32 s6, s98, 2
	s_lshl_b32 s27, s99, 2
	s_mov_b32 s7, 0
	s_addk_i32 s25, 0xf800
	s_add_i32 s26, s6, 0xffffff80
	s_addk_i32 s27, 0xff80
	s_mov_b32 s28, 0x3780000
	v_add_u32_e32 v9, v2, v3
	v_add_u32_e32 v11, v2, v11
	v_lshlrev_b32_e32 v2, 1, v0
	v_mov_b32_e32 v3, v1
	v_add_u32_e32 v12, 0x400, v8
	s_mov_b32 s29, s33

; __device__ __forceinline__ void phase_scan(KP kp_){ asm volatile("" : "+s"(kp_)); const Params p=load_params(kp_);
;     ...
;   int tid=ftid, lane=tid&63, wv=tid>>6, r=lane&15, kg=lane>>4;
;   for (int item=blockIdx.x; item<32; item+=gridDim.x){
;     int d=item&1, h=(item>>1)&7, b=item>>4;
;     char* tabase = d ? (p.ws+OFF_TAB) : (char*)p.out;
;     f32x4 Sacc[8];
;     _Pragma("unroll") for (int i=0;i<8;++i) Sacc[i]=f32x4{0.f,0.f,0.f,0.f};
;     u32x4 pq0A,pq1A,pk0A,pk1A,pv0A,pv1A,pt0A,pt1A,pt2A; float pgA;
;     u32x4 pq0B,pq1B,pk0B,pk1B,pv0B,pv1B,pt0B,pt1B,pt2B; float pgB;
;     ...
;     __syncthreads();
;     PREFETCH(A,0); FILL(A);
.LBB0_919:
	s_and_b64 vcc, exec, s[0:1]
	s_cbranch_vccz .LBB0_960
	s_mov_b64 exec, -1
	s_load_dwordx4 s[12:15], s[78:79], 0xd8
	s_and_b32 s44, s75, 31
	s_lshr_b32 s33, s75, 5
	s_and_b32 s2, s44, 1
	s_bfe_u32 s0, s44, 0x30001
	s_lshr_b32 s1, s44, 4
	v_and_b32_e32 v153, 63, v154
	v_and_b32_e32 v240, 15, v153
	v_lshrrev_b32_e32 v241, 4, v153
	v_lshrrev_b32_e32 v242, 6, v154
	v_mul_u32_u24_e32 v133, 0x110, v240
	v_readfirstlane_b32 s3, v242
	v_lshl_add_u32 v133, v241, 4, v133
	v_mul_u32_u24_e32 v134, 0x90, v240
	v_lshl_add_u32 v134, v241, 4, v134
	v_and_b32_e32 v245, 3, v242
	v_mul_u32_u24_e32 v243, 0x900, v245
	v_add_u32_e32 v135, v134, v243
	v_mul_u32_u24_e32 v243, 0x1200, v245
	v_add_u32_e32 v206, v134, v243
	v_lshl_add_u32 v136, v245, 6, v133
	v_add_u32_e32 v204, 0x19000, v136
	v_add_u32_e32 v205, 0x1d400, v136
	v_add_u32_e32 v200, 0x19000, v133
	v_add_u32_e32 v201, 0x1d400, v133
	v_add_u32_e32 v202, 0x10000, v134
	v_add_u32_e32 v203, 0x10000, v135
	v_lshlrev_b32_e32 v137, 4, v241
	v_lshrrev_b32_e32 v243, 4, v154
	v_and_b32_e32 v244, 15, v154
	v_lshrrev_b32_e32 v245, 2, v244
	v_lshlrev_b32_e32 v245, 6, v245
	v_and_b32_e32 v246, 1, v244
	v_lshl_add_u32 v245, v246, 5, v245
	v_bfe_u32 v246, v244, 1, 1
	v_lshl_add_u32 v245, v246, 3, v245
	v_mul_u32_u24_e32 v246, 0x110, v243
	v_add_u32_e32 v138, v246, v245
	v_add_u32_e32 v139, 0x2200, v138
	v_mul_u32_u24_e32 v149, 0x1800, v243
	v_lshl_add_u32 v149, v244, 4, v149
	v_lshrrev_b32_e32 v243, 3, v154
	v_and_b32_e32 v244, 7, v154
	v_lshrrev_b32_e32 v245, 2, v244
	v_lshlrev_b32_e32 v245, 6, v245
	v_and_b32_e32 v246, 1, v244
	v_lshl_add_u32 v245, v246, 5, v245
	v_bfe_u32 v246, v244, 1, 1
	v_lshl_add_u32 v245, v246, 3, v245
	v_mul_u32_u24_e32 v246, 0x90, v243
	v_add_u32_e32 v247, v246, v245
	v_lshl_add_u32 v146, v244, 4, v246
	v_add_u32_e32 v146, 0x10000, v146
	v_add_u32_e32 v140, 0x4400, v247
	v_add_u32_e32 v141, 0x6800, v247
	v_add_u32_e32 v142, 0x8c00, v247
	v_add_u32_e32 v143, 0xb000, v247
	v_add_u32_e32 v144, 0x14800, v247
	v_add_u32_e32 v145, 0xd400, v247
	v_lshlrev_b32_e32 v147, 2, v154
	v_lshlrev_b32_e32 v148, 4, v154
	v_lshlrev_b32_e32 v156, 10, v241
	v_lshl_add_u32 v156, v242, 5, v156
	v_lshl_add_u32 v156, v240, 1, v156
	s_lshl_b32 s44, s33, 7
	v_add_u32_e32 v156, s44, v156
	v_add_u32_e32 v157, 0x1000, v156
	v_add_u32_e32 v158, 0x2000, v156
	v_add_u32_e32 v159, 0x3000, v156
	v_mov_b32_e32 v0, 0
	v_mov_b32_e32 v1, 0
	v_mov_b32_e32 v2, 0
	v_mov_b32_e32 v3, 0
	v_mov_b32_e32 v4, 0
	v_mov_b32_e32 v5, 0
	v_mov_b32_e32 v6, 0
	v_mov_b32_e32 v7, 0
	v_mov_b32_e32 v8, 0
	v_mov_b32_e32 v9, 0
	v_mov_b32_e32 v10, 0
	v_mov_b32_e32 v11, 0
	v_mov_b32_e32 v12, 0
	v_mov_b32_e32 v13, 0
	v_mov_b32_e32 v14, 0
	v_mov_b32_e32 v15, 0
	v_mov_b32_e32 v16, 0
	v_mov_b32_e32 v17, 0
	v_mov_b32_e32 v18, 0
	v_mov_b32_e32 v19, 0
	v_mov_b32_e32 v20, 0
	v_mov_b32_e32 v21, 0
	v_mov_b32_e32 v22, 0
	v_mov_b32_e32 v23, 0
	v_mov_b32_e32 v24, 0
	v_mov_b32_e32 v25, 0
	v_mov_b32_e32 v26, 0
	v_mov_b32_e32 v27, 0
	v_mov_b32_e32 v28, 0
	v_mov_b32_e32 v29, 0
	v_mov_b32_e32 v30, 0
	v_mov_b32_e32 v31, 0
	s_waitcnt lgkmcnt(0)
	s_add_u32 s16, s14, 0xa5bd000
	s_addc_u32 s17, s15, 0
	s_cmp_eq_u32 s2, 0
	s_cselect_b32 s8, s12, s16
	s_cselect_b32 s9, s13, s17
	s_cselect_b32 s11, 63, 0
	s_lshl_b32 s16, s1, 3
	s_add_u32 s16, s16, s0
	s_mul_i32 s16, s16, 0x339000
	s_add_u32 s8, s8, s16
	s_addc_u32 s9, s9, 0
	s_lshl_b32 s16, s1, 5
	s_add_u32 s16, s16, s0
	s_mul_i32 s16, s16, 0xc000
	s_add_u32 s4, s14, 0x3fbd000
	s_addc_u32 s5, s15, 0
	s_add_u32 s4, s4, s16
	s_addc_u32 s5, s5, 0
	s_mul_i32 s16, s1, 0x3000000
	s_lshl_b32 s17, s0, 8
	s_add_u32 s16, s16, s17
	s_add_u32 s6, s14, 0x413d000
	s_addc_u32 s7, s15, 0
	s_add_u32 s6, s6, s16
	s_addc_u32 s7, s7, 0
	s_mov_b32 s12, 0
	s_sub_u32 s13, 3, s12
	s_sub_u32 s0, 0x87, s12
	s_cmp_lt_u32 s12, 4
	s_cselect_b32 s13, s13, s0
	s_cselect_b32 s18, 1, 0
	s_cmp_eq_u32 s2, 0
	s_cselect_b32 s12, s12, s13
	s_mul_i32 s13, s12, 0x60000
	s_cmp_eq_u32 s18, 1
	s_cselect_b32 s14, s4, s6
	s_cselect_b32 s15, s5, s7
	s_add_u32 s14, s14, s13
	s_addc_u32 s15, s15, 0
	s_mul_i32 s13, s12, 0x6400
	s_add_u32 s16, s8, s13
	s_addc_u32 s17, s9, 0
	s_mul_i32 s12, s18, 0x3800
	s_add_u32 s12, s12, 0x800
	s_mul_i32 s13, s18, 0x2e000
	s_sub_u32 s13, 0x30000, s13
	s_cmp_eq_u32 s18, 1
	s_cselect_b64 vcc, -1, 0
	s_add_u32 s36, s14, s12
	s_addc_u32 s37, s15, 0
	s_add_u32 s40, s36, s12
	s_addc_u32 s41, s37, 0
	s_add_u32 s38, s36, s13
	s_addc_u32 s39, s37, 0
	s_add_u32 s42, s40, s13
	s_addc_u32 s43, s41, 0
	s_add_u32 s46, s16, 0x2000
	s_addc_u32 s47, s17, 0
	v_cndmask_b32_e32 v151, v149, v148, vcc
	s_cmp_eq_u32 s33, 1
	s_cselect_b32 s40, s42, s40
	s_cselect_b32 s41, s43, s41
	s_mov_b32 s19, s18
	s_mov_b64 s[20:21], s[14:15]
	s_mov_b64 s[22:23], s[16:17]
	s_mul_i32 s13, s19, 0x2e000
	s_sub_u32 s13, 0x30000, s13
	s_cmp_eq_u32 s19, 1
	s_cselect_b64 vcc, -1, 0
	s_add_u32 s28, s20, s13
	s_addc_u32 s29, s21, 0
	s_add_u32 s30, s22, 0x4000
	s_addc_u32 s31, s23, 0
	s_add_u32 s34, s22, 0x6000
	s_addc_u32 s35, s23, 0
	v_cndmask_b32_e32 v150, v149, v148, vcc
	s_mov_b64 s[24:25], s[22:23]
	s_barrier
	global_load_dwordx4 v[96:99], v150, s[20:21]
	global_load_dwordx4 v[100:103], v150, s[28:29]
	global_load_dwordx4 v[128:131], v148, s[30:31]
	s_cmp_lg_u32 s3, 0
	s_cbranch_scc1 .Lmy_sc_nog0
	global_load_dword v132, v147, s[34:35]
; __device__ __forceinline__ unsigned pack2(float a, float b){ f32x2_t v={a,b}; bf16x2_t r=__builtin_convertvector(v,bf16x2_t); return __builtin_bit_cast(unsigned,r); }
; #define MF(a,b,c) __builtin_amdgcn_mfma_f32_16x16x32_bf16(a,b,c,0,0,0)
; __device__ __forceinline__ void phase_scan(KP kp_){ asm volatile("" : "+s"(kp_)); const Params p=load_params(kp_);
;     ...
;     PREFETCH(A,0); FILL(A);
;     __syncthreads();
;     for (int s2=0; s2<132; s2+=2){
;       { const int s=s2;
;         if (s+1<132) PREFETCH(A,s+1);
;       f32x4 wacc[4], vn[4];
;       _Pragma("unroll") for (int i=0;i<4;++i){ wacc[i]=f32x4{0.f,0.f,0.f,0.f}; vn[i]=f32x4{0.f,0.f,0.f,0.f}; }
;       _Pragma("unroll") for (int ks=0;ks<2;++ks){ int kb=(ks*32+kg*8)*2;
;         bf16x8 A=lds128(SKT+(wv*16+r)*144+kb);
;         bf16x8 Bv=lds128(SVT+(wv*16+r)*144+kb);
;         _Pragma("unroll") for (int t=0;t<4;++t){
;           wacc[t]=MF(A, lds128(STW+(t*16+r)*144+kb), wacc[t]);
;           vn[t]=MF(lds128(STU+(t*16+r)*144+kb), Bv, vn[t]); } }
;       _Pragma("unroll") for (int t=0;t<4;++t){ uint2 pk2; pk2.x=pack2(-wacc[t][0],-wacc[t][1]); pk2.y=pack2(-wacc[t][2],-wacc[t][3]);
;         *(uint2*)(smem+SWB+(t*16+r)*272+(wv*16+kg*4)*2)=pk2; }
.Lmy_sc_nog0:
	global_load_dwordx4 v[104:107], v151, s[36:37]
	global_load_dwordx4 v[108:111], v151, s[38:39]
	global_load_dwordx4 v[112:115], v151, s[40:41]
	global_load_dwordx4 v[120:123], v148, s[16:17]
	global_load_dwordx4 v[124:127], v148, s[46:47]
	s_waitcnt vmcnt(0)
	ds_write2_b64 v138, v[96:97], v[98:99] offset1:2
	ds_write2_b64 v139, v[100:101], v[102:103] offset1:2
	ds_write2_b64 v145, v[128:129], v[130:131] offset1:2
	s_cmp_lg_u32 s3, 0
	s_cbranch_scc1 .Lmy_sc_noe1
	v_mul_f32_e32 v240, 0x3fb8aa3b, v132
	v_readlane_b32 s12, v132, s11
	s_nop 0
	v_exp_f32_e32 v240, v240
	s_nop 1
	v_sub_f32_e32 v241, s12, v132
	v_mov_b32_e32 v242, s12
	s_nop 0
	v_mul_f32_e32 v241, 0x3fb8aa3b, v241
	v_mul_f32_e32 v242, 0x3fb8aa3b, v242
	s_nop 0
	v_exp_f32_e32 v241, v241
	v_exp_f32_e32 v242, v242
	s_nop 1
	ds_write_b32 v147, v240 offset:63488
	ds_write_b32 v147, v241 offset:63744
	ds_write_b32 v147, v242 offset:64000
.Lmy_sc_noe1:
	ds_write2_b64 v140, v[104:105], v[106:107] offset1:2
	ds_write2_b64 v141, v[108:109], v[110:111] offset1:2
	ds_write_b128 v146, v[112:115] offset:0
	ds_write2_b64 v144, v[120:121], v[122:123] offset1:2
	ds_write_b128 v146, v[124:127] offset:27648
	s_waitcnt lgkmcnt(0)
	s_barrier
	s_mov_b32 s12, 1
	s_sub_u32 s13, 3, s12
	s_sub_u32 s0, 0x87, s12
	s_cmp_lt_u32 s12, 4
	s_cselect_b32 s13, s13, s0
	s_cselect_b32 s18, 1, 0
	s_cmp_eq_u32 s2, 0
	s_cselect_b32 s12, s12, s13
	s_mul_i32 s13, s12, 0x60000
	s_cmp_eq_u32 s18, 1
	s_cselect_b32 s14, s4, s6
	s_cselect_b32 s15, s5, s7
	s_add_u32 s14, s14, s13
	s_addc_u32 s15, s15, 0
	s_mul_i32 s13, s12, 0x6400
	s_add_u32 s16, s8, s13
	s_addc_u32 s17, s9, 0
	s_mul_i32 s12, s18, 0x3800
	s_add_u32 s12, s12, 0x800
	s_mul_i32 s13, s18, 0x2e000
	s_sub_u32 s13, 0x30000, s13
	s_cmp_eq_u32 s18, 1
	s_cselect_b64 vcc, -1, 0
	s_add_u32 s36, s14, s12
	s_addc_u32 s37, s15, 0
	s_add_u32 s40, s36, s12
	s_addc_u32 s41, s37, 0
	s_add_u32 s38, s36, s13
	s_addc_u32 s39, s37, 0
	s_add_u32 s42, s40, s13
	s_addc_u32 s43, s41, 0
	s_add_u32 s46, s16, 0x2000
	s_addc_u32 s47, s17, 0
	v_cndmask_b32_e32 v151, v149, v148, vcc
	s_cmp_eq_u32 s33, 1
	s_cselect_b32 s40, s42, s40
	s_cselect_b32 s41, s43, s41
	global_load_dwordx4 v[104:107], v151, s[36:37]
	global_load_dwordx4 v[108:111], v151, s[38:39]
	global_load_dwordx4 v[112:115], v151, s[40:41]
	global_load_dwordx4 v[120:123], v148, s[16:17]
	global_load_dwordx4 v[124:127], v148, s[46:47]
	s_cmp_ge_u32 s3, 4
	s_cbranch_scc1 .Lmy_sc_ph2
	ds_read_b128 v[216:219], v203 offset:0
	ds_read_b128 v[220:223], v203 offset:64
	ds_read_b128 v[160:163], v202 offset:27648
	ds_read_b128 v[164:167], v202 offset:29952
	ds_read_b128 v[168:171], v202 offset:32256
	ds_read_b128 v[172:175], v202 offset:34560
	ds_read_b128 v[176:179], v202 offset:27712
	ds_read_b128 v[180:183], v202 offset:30016
	ds_read_b128 v[184:187], v202 offset:32320
	ds_read_b128 v[188:191], v202 offset:34624
	s_waitcnt lgkmcnt(7)
	v_mfma_f32_16x16x32_bf16 v[48:51], v[160:163], v[216:219], 0
	s_waitcnt lgkmcnt(6)
	v_mfma_f32_16x16x32_bf16 v[52:55], v[164:167], v[216:219], 0
	s_waitcnt lgkmcnt(5)
	v_mfma_f32_16x16x32_bf16 v[56:59], v[168:171], v[216:219], 0
	s_waitcnt lgkmcnt(4)
	v_mfma_f32_16x16x32_bf16 v[60:63], v[172:175], v[216:219], 0
	s_waitcnt lgkmcnt(3)
	v_mfma_f32_16x16x32_bf16 v[48:51], v[176:179], v[220:223], v[48:51]
	s_waitcnt lgkmcnt(2)
	v_mfma_f32_16x16x32_bf16 v[52:55], v[180:183], v[220:223], v[52:55]
	s_waitcnt lgkmcnt(1)
	v_mfma_f32_16x16x32_bf16 v[56:59], v[184:187], v[220:223], v[56:59]
	s_waitcnt lgkmcnt(0)
	v_mfma_f32_16x16x32_bf16 v[60:63], v[188:191], v[220:223], v[60:63]
	s_waitcnt lgkmcnt(0)
	s_branch .Lmy_sc_pj2
.Lmy_sc_ph2:
	ds_read_b128 v[208:211], v206 offset:17408
	ds_read_b128 v[212:215], v206 offset:17472
	ds_read_b128 v[216:219], v206 offset:19712
	ds_read_b128 v[220:223], v206 offset:19776
	ds_read_b128 v[160:163], v202 offset:18432
	ds_read_b128 v[164:167], v202 offset:20736
	ds_read_b128 v[168:171], v202 offset:23040
	ds_read_b128 v[172:175], v202 offset:25344
	ds_read_b128 v[176:179], v202 offset:18496
	ds_read_b128 v[180:183], v202 offset:20800
	ds_read_b128 v[184:187], v202 offset:23104
	ds_read_b128 v[188:191], v202 offset:25408
	s_waitcnt lgkmcnt(11)
	s_waitcnt lgkmcnt(7)
	v_mfma_f32_16x16x32_bf16 v[0:3], v[208:211], v[160:163], 0
	v_mfma_f32_16x16x32_bf16 v[16:19], v[216:219], v[160:163], 0
	s_waitcnt lgkmcnt(6)
	v_mfma_f32_16x16x32_bf16 v[4:7], v[208:211], v[164:167], 0
	v_mfma_f32_16x16x32_bf16 v[20:23], v[216:219], v[164:167], 0
	s_waitcnt lgkmcnt(5)
	v_mfma_f32_16x16x32_bf16 v[8:11], v[208:211], v[168:171], 0
	v_mfma_f32_16x16x32_bf16 v[24:27], v[216:219], v[168:171], 0
	s_waitcnt lgkmcnt(4)
	v_mfma_f32_16x16x32_bf16 v[12:15], v[208:211], v[172:175], 0
	v_mfma_f32_16x16x32_bf16 v[28:31], v[216:219], v[172:175], 0
	s_waitcnt lgkmcnt(3)
	v_mfma_f32_16x16x32_bf16 v[0:3], v[212:215], v[176:179], v[0:3]
	v_mfma_f32_16x16x32_bf16 v[16:19], v[220:223], v[176:179], v[16:19]
	s_waitcnt lgkmcnt(2)
	v_mfma_f32_16x16x32_bf16 v[4:7], v[212:215], v[180:183], v[4:7]
	v_mfma_f32_16x16x32_bf16 v[20:23], v[220:223], v[180:183], v[20:23]
	s_waitcnt lgkmcnt(1)
	v_mfma_f32_16x16x32_bf16 v[8:11], v[212:215], v[184:187], v[8:11]
	v_mfma_f32_16x16x32_bf16 v[24:27], v[220:223], v[184:187], v[24:27]
	s_waitcnt lgkmcnt(0)
	v_mfma_f32_16x16x32_bf16 v[12:15], v[212:215], v[188:191], v[12:15]
	v_mfma_f32_16x16x32_bf16 v[28:31], v[220:223], v[188:191], v[28:31]
	v_cvt_pk_bf16_f32 v244, -v0, -v1
	v_cvt_pk_bf16_f32 v245, -v2, -v3
	ds_write_b64 v204, v[244:245] offset:0
	v_cvt_pk_bf16_f32 v250, -v16, -v17
	v_cvt_pk_bf16_f32 v251, -v18, -v19
	ds_write_b64 v204, v[250:251] offset:8
	v_cvt_pk_bf16_f32 v244, -v4, -v5
	v_cvt_pk_bf16_f32 v245, -v6, -v7
	ds_write_b64 v204, v[244:245] offset:4352
	v_cvt_pk_bf16_f32 v250, -v20, -v21
	v_cvt_pk_bf16_f32 v251, -v22, -v23
	ds_write_b64 v204, v[250:251] offset:4360
	v_cvt_pk_bf16_f32 v244, -v8, -v9
	v_cvt_pk_bf16_f32 v245, -v10, -v11
	ds_write_b64 v204, v[244:245] offset:8704
	v_cvt_pk_bf16_f32 v250, -v24, -v25
	v_cvt_pk_bf16_f32 v251, -v26, -v27
	ds_write_b64 v204, v[250:251] offset:8712
	v_cvt_pk_bf16_f32 v244, -v12, -v13
	v_cvt_pk_bf16_f32 v245, -v14, -v15
	ds_write_b64 v204, v[244:245] offset:13056
	v_cvt_pk_bf16_f32 v250, -v28, -v29
	v_cvt_pk_bf16_f32 v251, -v30, -v31
	ds_write_b64 v204, v[250:251] offset:13064
	s_waitcnt lgkmcnt(0)
; __device__ __forceinline__ unsigned pack2(float a, float b){ f32x2_t v={a,b}; bf16x2_t r=__builtin_convertvector(v,bf16x2_t); return __builtin_bit_cast(unsigned,r); }
; __device__ __forceinline__ bf16x8 packfrag(f32x4 d0, f32x4 d1){ u32x4 t={pack2(d0[0],d0[1]),pack2(d0[2],d0[3]),pack2(d1[0],d1[1]),pack2(d1[2],d1[3])}; return __builtin_bit_cast(bf16x8,t); }
; #define MF(a,b,c) __builtin_amdgcn_mfma_f32_16x16x32_bf16(a,b,c,0,0,0)
; __device__ __forceinline__ void phase_scan(KP kp_){ asm volatile("" : "+s"(kp_)); const Params p=load_params(kp_);
;     ...
;     for (int s2=0; s2<132; s2+=2){
;       { const int s=s2;
;         if (s+1<132) PREFETCH(A,s+1);
;       f32x4 wacc[4], vn[4];
;       _Pragma("unroll") for (int i=0;i<4;++i){ wacc[i]=f32x4{0.f,0.f,0.f,0.f}; vn[i]=f32x4{0.f,0.f,0.f,0.f}; }
;       _Pragma("unroll") for (int ks=0;ks<2;++ks){ int kb=(ks*32+kg*8)*2;
;         bf16x8 A=lds128(SKT+(wv*16+r)*144+kb);
;         bf16x8 Bv=lds128(SVT+(wv*16+r)*144+kb);
;         _Pragma("unroll") for (int t=0;t<4;++t){
;           wacc[t]=MF(A, lds128(STW+(t*16+r)*144+kb), wacc[t]);
;           vn[t]=MF(lds128(STU+(t*16+r)*144+kb), Bv, vn[t]); } }
;       _Pragma("unroll") for (int t=0;t<4;++t){ uint2 pk2; pk2.x=pack2(-wacc[t][0],-wacc[t][1]); pk2.y=pack2(-wacc[t][2],-wacc[t][3]);
;         *(uint2*)(smem+SWB+(t*16+r)*272+(wv*16+kg*4)*2)=pk2; }
;       __syncthreads();
;       bf16x8 Sf[4];
;       _Pragma("unroll") for (int q=0;q<4;++q) Sf[q]=packfrag(Sacc[2*q],Sacc[2*q+1]);
;       f32x4 oacc[4];
;       _Pragma("unroll") for (int i=0;i<4;++i) oacc[i]=f32x4{0.f,0.f,0.f,0.f};
;       _Pragma("unroll") for (int q=0;q<4;++q){ int kb=(32*q+kg*4)*2;
;         _Pragma("unroll") for (int t=0;t<4;++t){
;           vn[t]=MF(lds64x2(SWB+(t*16+r)*272+kb), Sf[q], vn[t]);
.Lmy_sc_pj2:
	s_waitcnt lgkmcnt(0)
	s_barrier
	s_waitcnt vmcnt(0)
	ds_write2_b64 v142, v[104:105], v[106:107] offset1:2
	ds_write2_b64 v143, v[108:109], v[110:111] offset1:2
	ds_write_b128 v146, v[112:115] offset:0
	ds_write2_b64 v144, v[120:121], v[122:123] offset1:2
	ds_write_b128 v146, v[124:127] offset:27648
	s_waitcnt lgkmcnt(0)
	s_mov_b32 s19, s18
	s_mov_b64 s[20:21], s[14:15]
	s_mov_b64 s[22:23], s[16:17]
	s_barrier
	s_mov_b32 s10, 0
.Lmy_scan_loop:
	s_add_u32 s12, s10, 2
	s_min_u32 s12, s12, 0x83
	s_sub_u32 s13, 3, s12
	s_sub_u32 s0, 0x87, s12
	s_cmp_lt_u32 s12, 4
	s_cselect_b32 s13, s13, s0
	s_cselect_b32 s18, 1, 0
	s_cmp_eq_u32 s2, 0
	s_cselect_b32 s12, s12, s13
	s_mul_i32 s13, s12, 0x60000
	s_cmp_eq_u32 s18, 1
	s_cselect_b32 s14, s4, s6
	s_cselect_b32 s15, s5, s7
	s_add_u32 s14, s14, s13
	s_addc_u32 s15, s15, 0
	s_mul_i32 s13, s12, 0x6400
	s_add_u32 s16, s8, s13
	s_addc_u32 s17, s9, 0
	s_mul_i32 s12, s18, 0x3800
	s_add_u32 s12, s12, 0x800
	s_mul_i32 s13, s18, 0x2e000
	s_sub_u32 s13, 0x30000, s13
	s_cmp_eq_u32 s18, 1
	s_cselect_b64 vcc, -1, 0
	s_add_u32 s36, s14, s12
	s_addc_u32 s37, s15, 0
	s_add_u32 s40, s36, s12
	s_addc_u32 s41, s37, 0
	s_add_u32 s38, s36, s13
	s_addc_u32 s39, s37, 0
	s_add_u32 s42, s40, s13
	s_addc_u32 s43, s41, 0
	s_add_u32 s46, s16, 0x2000
	s_addc_u32 s47, s17, 0
	v_cndmask_b32_e32 v151, v149, v148, vcc
	s_cmp_eq_u32 s33, 1
	s_cselect_b32 s40, s42, s40
	s_cselect_b32 s41, s43, s41
	s_mul_i32 s13, s19, 0x2e000
	s_sub_u32 s13, 0x30000, s13
	s_cmp_eq_u32 s19, 1
	s_cselect_b64 vcc, -1, 0
	s_add_u32 s28, s20, s13
	s_addc_u32 s29, s21, 0
	s_add_u32 s30, s22, 0x4000
	s_addc_u32 s31, s23, 0
	s_add_u32 s34, s22, 0x6000
	s_addc_u32 s35, s23, 0
	v_cndmask_b32_e32 v150, v149, v148, vcc
	global_load_dwordx4 v[96:99], v150, s[20:21]
	global_load_dwordx4 v[100:103], v150, s[28:29]
	global_load_dwordx4 v[128:131], v148, s[30:31]
	s_cmp_lg_u32 s3, 0
	s_cbranch_scc1 .Lmy_sc_nog3
	global_load_dword v132, v147, s[34:35]
.Lmy_sc_nog3:
	global_load_dwordx4 v[104:107], v151, s[36:37]
	global_load_dwordx4 v[108:111], v151, s[38:39]
	global_load_dwordx4 v[112:115], v151, s[40:41]
	global_load_dwordx4 v[120:123], v148, s[16:17]
	global_load_dwordx4 v[124:127], v148, s[46:47]
	s_cmp_ge_u32 s3, 4
	s_cbranch_scc1 .Lmy_sc_h4
	ds_read_b32 v152, v137 offset:64000
	ds_read_b128 v[160:163], v200 offset:0
	ds_read_b128 v[164:167], v200 offset:64
	ds_read_b128 v[168:171], v200 offset:128
	ds_read_b128 v[172:175], v200 offset:192
	ds_read_b128 v[176:179], v200 offset:4352
	ds_read_b128 v[180:183], v200 offset:4416
	ds_read_b128 v[184:187], v200 offset:4480
	ds_read_b128 v[188:191], v200 offset:4544
	ds_read_b128 v[224:227], v137 offset:63744
	ds_read_b128 v[228:231], v137 offset:63808
	v_cvt_pk_bf16_f32 v32, v0, v1
	v_cvt_pk_bf16_f32 v33, v2, v3
	v_cvt_pk_bf16_f32 v34, v4, v5
	v_cvt_pk_bf16_f32 v35, v6, v7
	v_cvt_pk_bf16_f32 v36, v8, v9
	v_cvt_pk_bf16_f32 v37, v10, v11
	v_cvt_pk_bf16_f32 v38, v12, v13
	v_cvt_pk_bf16_f32 v39, v14, v15
	v_cvt_pk_bf16_f32 v40, v16, v17
	v_cvt_pk_bf16_f32 v41, v18, v19
	v_cvt_pk_bf16_f32 v42, v20, v21
	v_cvt_pk_bf16_f32 v43, v22, v23
	v_cvt_pk_bf16_f32 v44, v24, v25
	v_cvt_pk_bf16_f32 v45, v26, v27
	v_cvt_pk_bf16_f32 v46, v28, v29
	v_cvt_pk_bf16_f32 v47, v30, v31
	s_waitcnt lgkmcnt(9)
	v_mfma_f32_16x16x32_bf16 v[48:51], v[160:163], v[32:35], v[48:51]
	ds_read_b128 v[192:195], v200 offset:8704
	v_mul_f32_e32 v0, v152, v0
	v_mul_f32_e32 v1, v152, v1
	s_waitcnt lgkmcnt(9)
	v_mfma_f32_16x16x32_bf16 v[48:51], v[164:167], v[36:39], v[48:51]
	ds_read_b128 v[196:199], v200 offset:8768
	v_mul_f32_e32 v2, v152, v2
	v_mul_f32_e32 v3, v152, v3
	s_waitcnt lgkmcnt(9)
	v_mfma_f32_16x16x32_bf16 v[48:51], v[168:171], v[40:43], v[48:51]
	ds_read_b128 v[160:163], v200 offset:8832
	v_mul_f32_e32 v4, v152, v4
	v_mul_f32_e32 v5, v152, v5
	ds_read_b128 v[232:235], v137 offset:63872
	s_waitcnt lgkmcnt(10)
	v_mfma_f32_16x16x32_bf16 v[48:51], v[172:175], v[44:47], v[48:51]
	ds_read_b128 v[164:167], v200 offset:8896
	v_mul_f32_e32 v6, v152, v6
	v_mul_f32_e32 v7, v152, v7
	s_waitcnt lgkmcnt(10)
	v_mfma_f32_16x16x32_bf16 v[52:55], v[176:179], v[32:35], v[52:55]
	ds_read_b128 v[168:171], v200 offset:13056
	v_mul_f32_e32 v8, v152, v8
	v_mul_f32_e32 v9, v152, v9
	ds_read_b128 v[236:239], v137 offset:63936
	s_waitcnt lgkmcnt(11)
	v_mfma_f32_16x16x32_bf16 v[52:55], v[180:183], v[36:39], v[52:55]
	ds_read_b128 v[172:175], v200 offset:13120
	v_mul_f32_e32 v10, v152, v10
	v_mul_f32_e32 v11, v152, v11
	s_waitcnt lgkmcnt(11)
	v_mfma_f32_16x16x32_bf16 v[52:55], v[184:187], v[40:43], v[52:55]
	ds_read_b128 v[176:179], v200 offset:13184
	v_mul_f32_e32 v12, v152, v12
	v_mul_f32_e32 v13, v152, v13
	s_waitcnt lgkmcnt(11)
	v_mfma_f32_16x16x32_bf16 v[52:55], v[188:191], v[44:47], v[52:55]
	ds_read_b128 v[180:183], v200 offset:13248
	v_mul_f32_e32 v14, v152, v14
	v_mul_f32_e32 v15, v152, v15
	s_waitcnt lgkmcnt(9)
	v_mfma_f32_16x16x32_bf16 v[56:59], v[192:195], v[32:35], v[56:59]
	ds_read_b128 v[184:187], v133 offset:0
	v_mul_f32_e32 v16, v152, v16
	v_mul_f32_e32 v17, v152, v17
	s_waitcnt lgkmcnt(9)
	v_mfma_f32_16x16x32_bf16 v[56:59], v[196:199], v[36:39], v[56:59]
	ds_read_b128 v[188:191], v133 offset:64
	v_mul_f32_e32 v18, v152, v18
	v_mul_f32_e32 v19, v152, v19
	s_waitcnt lgkmcnt(9)
	v_mfma_f32_16x16x32_bf16 v[56:59], v[160:163], v[40:43], v[56:59]
	ds_read_b128 v[192:195], v133 offset:128
	v_mul_f32_e32 v20, v152, v20
	v_mul_f32_e32 v21, v152, v21
	s_waitcnt lgkmcnt(8)
	v_mfma_f32_16x16x32_bf16 v[56:59], v[164:167], v[44:47], v[56:59]
	ds_read_b128 v[196:199], v133 offset:192
	v_mul_f32_e32 v22, v152, v22
	v_mul_f32_e32 v23, v152, v23
	s_waitcnt lgkmcnt(8)
; __device__ __forceinline__ bf16x8 packfrag(f32x4 d0, f32x4 d1){ u32x4 t={pack2(d0[0],d0[1]),pack2(d0[2],d0[3]),pack2(d1[0],d1[1]),pack2(d1[2],d1[3])}; return __builtin_bit_cast(bf16x8,t); }
; #define MF(a,b,c) __builtin_amdgcn_mfma_f32_16x16x32_bf16(a,b,c,0,0,0)
; __device__ __forceinline__ void phase_scan(KP kp_){ asm volatile("" : "+s"(kp_)); const Params p=load_params(kp_);
;     ...
;       _Pragma("unroll") for (int q=0;q<4;++q){ int kb=(32*q+kg*4)*2;
;         _Pragma("unroll") for (int t=0;t<4;++t){
;           vn[t]=MF(lds64x2(SWB+(t*16+r)*272+kb), Sf[q], vn[t]);
;           oacc[t]=MF(lds64x2(SQ+(t*16+r)*272+kb), Sf[q], oacc[t]); } }
;       const float* gcs=(const float*)(smem+SGC);
;       float gl = d ? gcs[0] : gcs[63];
;       float gam=__expf(gl);
;       f32x4 vs[4];
;       _Pragma("unroll") for (int t=0;t<4;++t){ float4 g4=*(const float4*)(gcs+t*16+kg*4);
;         oacc[t][0]*=__expf(g4.x); oacc[t][1]*=__expf(g4.y); oacc[t][2]*=__expf(g4.z); oacc[t][3]*=__expf(g4.w);
;         vs[t][0]=vn[t][0]*__expf(gl-g4.x); vs[t][1]=vn[t][1]*__expf(gl-g4.y); vs[t][2]=vn[t][2]*__expf(gl-g4.z); vs[t][3]=vn[t][3]*__expf(gl-g4.w); }
;       bf16x8 Vf[2], Wf[2];
;       _Pragma("unroll") for (int q=0;q<2;++q){ Vf[q]=packfrag(vn[2*q],vn[2*q+1]); Wf[q]=packfrag(vs[2*q],vs[2*q+1]); }
;       _Pragma("unroll") for (int q=0;q<2;++q){ int kb=(32*q+kg*4)*2;
;         _Pragma("unroll") for (int t=0;t<4;++t) oacc[t]=MF(lds64x2(SAT+(t*16+r)*144+kb), Vf[q], oacc[t]); }
;       _Pragma("unroll") for (int m8=0;m8<8;++m8){ Sacc[m8][0]*=gam; Sacc[m8][1]*=gam; Sacc[m8][2]*=gam; Sacc[m8][3]*=gam; }
;       _Pragma("unroll") for (int q=0;q<2;++q){ int kb=(32*q+kg*4)*2;
;         _Pragma("unroll") for (int m8=0;m8<8;++m8) Sacc[m8]=MF(lds64x2(SKT+(m8*16+r)*144+kb), Wf[q], Sacc[m8]); }
	v_mfma_f32_16x16x32_bf16 v[60:63], v[168:171], v[32:35], v[60:63]
	ds_read_b128 v[160:163], v133 offset:4352
	v_mul_f32_e32 v24, v152, v24
	v_mul_f32_e32 v25, v152, v25
	s_waitcnt lgkmcnt(7)
	v_mfma_f32_16x16x32_bf16 v[60:63], v[172:175], v[36:39], v[60:63]
	ds_read_b128 v[164:167], v133 offset:4416
	v_mul_f32_e32 v26, v152, v26
	v_mul_f32_e32 v27, v152, v27
	s_waitcnt lgkmcnt(7)
	v_mfma_f32_16x16x32_bf16 v[60:63], v[176:179], v[40:43], v[60:63]
	ds_read_b128 v[168:171], v133 offset:4480
	v_mul_f32_e32 v28, v152, v28
	v_mul_f32_e32 v29, v152, v29
	s_waitcnt lgkmcnt(7)
	v_mfma_f32_16x16x32_bf16 v[60:63], v[180:183], v[44:47], v[60:63]
	ds_read_b128 v[172:175], v133 offset:4544
	v_mul_f32_e32 v30, v152, v30
	v_mul_f32_e32 v31, v152, v31
	s_waitcnt lgkmcnt(7)
	v_mfma_f32_16x16x32_bf16 v[64:67], v[184:187], v[32:35], 0
	ds_read_b128 v[176:179], v133 offset:8704
	v_mul_f32_e32 v224, v48, v224
	v_mul_f32_e32 v225, v49, v225
	s_waitcnt lgkmcnt(7)
	v_mfma_f32_16x16x32_bf16 v[64:67], v[188:191], v[36:39], v[64:67]
	ds_read_b128 v[180:183], v133 offset:8768
	v_mul_f32_e32 v226, v50, v226
	v_mul_f32_e32 v227, v51, v227
	s_waitcnt lgkmcnt(7)
	v_mfma_f32_16x16x32_bf16 v[64:67], v[192:195], v[40:43], v[64:67]
	ds_read_b128 v[184:187], v133 offset:8832
	v_cvt_pk_bf16_f32 v88, v48, v49
	v_cvt_pk_bf16_f32 v89, v50, v51
	s_waitcnt lgkmcnt(7)
	v_mfma_f32_16x16x32_bf16 v[64:67], v[196:199], v[44:47], v[64:67]
	ds_read_b128 v[188:191], v133 offset:8896
	v_cvt_pk_bf16_f32 v80, v224, v225
	v_cvt_pk_bf16_f32 v81, v226, v227
	s_waitcnt lgkmcnt(7)
	v_mfma_f32_16x16x32_bf16 v[68:71], v[160:163], v[32:35], 0
	ds_read_b128 v[192:195], v133 offset:13056
	v_mul_f32_e32 v228, v52, v228
	v_mul_f32_e32 v229, v53, v229
	s_waitcnt lgkmcnt(7)
	v_mfma_f32_16x16x32_bf16 v[68:71], v[164:167], v[36:39], v[68:71]
	ds_read_b128 v[196:199], v133 offset:13120
	v_mul_f32_e32 v230, v54, v230
	v_mul_f32_e32 v231, v55, v231
	s_waitcnt lgkmcnt(7)
	v_mfma_f32_16x16x32_bf16 v[68:71], v[168:171], v[40:43], v[68:71]
	ds_read_b128 v[160:163], v133 offset:13184
	v_cvt_pk_bf16_f32 v90, v52, v53
	v_cvt_pk_bf16_f32 v91, v54, v55
	s_waitcnt lgkmcnt(7)
	v_mfma_f32_16x16x32_bf16 v[68:71], v[172:175], v[44:47], v[68:71]
	ds_read_b128 v[164:167], v133 offset:13248
	v_cvt_pk_bf16_f32 v82, v228, v229
	v_cvt_pk_bf16_f32 v83, v230, v231
	s_waitcnt lgkmcnt(7)
	v_mfma_f32_16x16x32_bf16 v[72:75], v[176:179], v[32:35], 0
	ds_read_b128 v[168:171], v134 offset:17408
	v_mul_f32_e32 v232, v56, v232
	v_mul_f32_e32 v233, v57, v233
	s_waitcnt lgkmcnt(7)
	v_mfma_f32_16x16x32_bf16 v[72:75], v[180:183], v[36:39], v[72:75]
	ds_read_b128 v[172:175], v134 offset:19712
	v_mul_f32_e32 v234, v58, v234
	v_mul_f32_e32 v235, v59, v235
	s_waitcnt lgkmcnt(7)
	v_mfma_f32_16x16x32_bf16 v[72:75], v[184:187], v[40:43], v[72:75]
	ds_read_b128 v[176:179], v134 offset:22016
	v_cvt_pk_bf16_f32 v92, v56, v57
	v_cvt_pk_bf16_f32 v93, v58, v59
	s_waitcnt lgkmcnt(7)
	v_mfma_f32_16x16x32_bf16 v[72:75], v[188:191], v[44:47], v[72:75]
	ds_read_b128 v[180:183], v134 offset:24320
	v_cvt_pk_bf16_f32 v84, v232, v233
	v_cvt_pk_bf16_f32 v85, v234, v235
	s_waitcnt lgkmcnt(7)
	v_mfma_f32_16x16x32_bf16 v[76:79], v[192:195], v[32:35], 0
	ds_read_b128 v[184:187], v134 offset:26624
	v_mul_f32_e32 v236, v60, v236
	v_mul_f32_e32 v237, v61, v237
	s_waitcnt lgkmcnt(7)
	v_mfma_f32_16x16x32_bf16 v[76:79], v[196:199], v[36:39], v[76:79]
	ds_read_b128 v[188:191], v134 offset:28928
	v_mul_f32_e32 v238, v62, v238
	v_mul_f32_e32 v239, v63, v239
	s_waitcnt lgkmcnt(7)
	v_mfma_f32_16x16x32_bf16 v[76:79], v[160:163], v[40:43], v[76:79]
	ds_read_b128 v[192:195], v134 offset:31232
	v_cvt_pk_bf16_f32 v94, v60, v61
	v_cvt_pk_bf16_f32 v95, v62, v63
	s_waitcnt lgkmcnt(7)
	v_mfma_f32_16x16x32_bf16 v[76:79], v[164:167], v[44:47], v[76:79]
	ds_read_b128 v[196:199], v134 offset:33536
	v_cvt_pk_bf16_f32 v86, v236, v237
	v_cvt_pk_bf16_f32 v87, v238, v239
	s_waitcnt lgkmcnt(7)
	v_mfma_f32_16x16x32_bf16 v[0:3], v[168:171], v[80:83], v[0:3]
	ds_read_b128 v[160:163], v134 offset:17472
	ds_read_b128 v[224:227], v137 offset:63488
	s_waitcnt lgkmcnt(8)
	v_mfma_f32_16x16x32_bf16 v[4:7], v[172:175], v[80:83], v[4:7]
	ds_read_b128 v[164:167], v134 offset:19776
	ds_read_b128 v[228:231], v137 offset:63552
	s_waitcnt lgkmcnt(9)
	v_mfma_f32_16x16x32_bf16 v[8:11], v[176:179], v[80:83], v[8:11]
	ds_read_b128 v[168:171], v134 offset:22080
	ds_read_b128 v[232:235], v137 offset:63616
	s_waitcnt lgkmcnt(10)
	v_mfma_f32_16x16x32_bf16 v[12:15], v[180:183], v[80:83], v[12:15]
	ds_read_b128 v[172:175], v134 offset:24384
	ds_read_b128 v[236:239], v137 offset:63680
	s_waitcnt lgkmcnt(11)
	v_mfma_f32_16x16x32_bf16 v[16:19], v[184:187], v[80:83], v[16:19]
	ds_read_b128 v[176:179], v134 offset:26688
	s_waitcnt lgkmcnt(11)
	v_mfma_f32_16x16x32_bf16 v[20:23], v[188:191], v[80:83], v[20:23]
	ds_read_b128 v[180:183], v134 offset:28992
	s_waitcnt lgkmcnt(11)
	v_mfma_f32_16x16x32_bf16 v[24:27], v[192:195], v[80:83], v[24:27]
	ds_read_b128 v[184:187], v134 offset:31296
	s_waitcnt lgkmcnt(11)
	v_mfma_f32_16x16x32_bf16 v[28:31], v[196:199], v[80:83], v[28:31]
	ds_read_b128 v[188:191], v134 offset:33600
	s_waitcnt lgkmcnt(11)
	v_mfma_f32_16x16x32_bf16 v[0:3], v[160:163], v[84:87], v[0:3]
	ds_read_b128 v[192:195], v134 offset:54272
	s_waitcnt lgkmcnt(11)
	v_mul_f32_e32 v64, v64, v224
	v_mul_f32_e32 v65, v65, v225
	s_waitcnt lgkmcnt(10)
	v_mfma_f32_16x16x32_bf16 v[4:7], v[164:167], v[84:87], v[4:7]
	ds_read_b128 v[196:199], v134 offset:56576
	v_mul_f32_e32 v66, v66, v226
	v_mul_f32_e32 v67, v67, v227
	s_waitcnt lgkmcnt(9)
	v_mfma_f32_16x16x32_bf16 v[8:11], v[168:171], v[84:87], v[8:11]
	ds_read_b128 v[160:163], v134 offset:58880
	v_mul_f32_e32 v68, v68, v228
	v_mul_f32_e32 v69, v69, v229
	s_waitcnt lgkmcnt(8)
; __device__ __forceinline__ unsigned pack2(float a, float b){ f32x2_t v={a,b}; bf16x2_t r=__builtin_convertvector(v,bf16x2_t); return __builtin_bit_cast(unsigned,r); }
; #define MF(a,b,c) __builtin_amdgcn_mfma_f32_16x16x32_bf16(a,b,c,0,0,0)
; __device__ __forceinline__ void phase_scan(KP kp_){ asm volatile("" : "+s"(kp_)); const Params p=load_params(kp_);
;     ...
;       _Pragma("unroll") for (int ks=0;ks<2;++ks){ int kb=(ks*32+kg*8)*2;
;         bf16x8 A=lds128(SKT+(wv*16+r)*144+kb);
;         bf16x8 Bv=lds128(SVT+(wv*16+r)*144+kb);
;         _Pragma("unroll") for (int t=0;t<4;++t){
;           wacc[t]=MF(A, lds128(STW+(t*16+r)*144+kb), wacc[t]);
;           vn[t]=MF(lds128(STU+(t*16+r)*144+kb), Bv, vn[t]); } }
;       _Pragma("unroll") for (int t=0;t<4;++t){ uint2 pk2; pk2.x=pack2(-wacc[t][0],-wacc[t][1]); pk2.y=pack2(-wacc[t][2],-wacc[t][3]);
;         *(uint2*)(smem+SWB+(t*16+r)*272+(wv*16+kg*4)*2)=pk2; }
;     ...
;       _Pragma("unroll") for (int q=0;q<2;++q){ int kb=(32*q+kg*4)*2;
;         _Pragma("unroll") for (int t=0;t<4;++t) oacc[t]=MF(lds64x2(SAT+(t*16+r)*144+kb), Vf[q], oacc[t]); }
;       _Pragma("unroll") for (int m8=0;m8<8;++m8){ Sacc[m8][0]*=gam; Sacc[m8][1]*=gam; Sacc[m8][2]*=gam; Sacc[m8][3]*=gam; }
;       _Pragma("unroll") for (int q=0;q<2;++q){ int kb=(32*q+kg*4)*2;
;         _Pragma("unroll") for (int m8=0;m8<8;++m8) Sacc[m8]=MF(lds64x2(SKT+(m8*16+r)*144+kb), Wf[q], Sacc[m8]); }
;       if (s>=4){ int cidx=4+(d?131-s:s-4); char* op=tabase+(size_t)((b*8+h)*132+cidx)*TA_STRIDE;
;         _Pragma("unroll") for (int t=0;t<4;++t) _Pragma("unroll") for (int j=0;j<4;++j)
;           *(u16*)(op+((t*16+kg*4+j)*128+wv*16+r)*2)=f2bf(oacc[t][j]); }
;         __syncthreads();
;         FILL(A);
;         __syncthreads();
;       }
;       { const int s=s2+1;
;         if (s+1<132) PREFETCH(A,s+1);
	v_mfma_f32_16x16x32_bf16 v[12:15], v[172:175], v[84:87], v[12:15]
	ds_read_b128 v[164:167], v134 offset:61184
	v_mul_f32_e32 v70, v70, v230
	v_mul_f32_e32 v71, v71, v231
	s_waitcnt lgkmcnt(7)
	v_mfma_f32_16x16x32_bf16 v[16:19], v[176:179], v[84:87], v[16:19]
	ds_read_b128 v[168:171], v134 offset:54336
	v_mul_f32_e32 v72, v72, v232
	v_mul_f32_e32 v73, v73, v233
	ds_read_b128 v[216:219], v203 offset:0
	s_waitcnt lgkmcnt(8)
	v_mfma_f32_16x16x32_bf16 v[20:23], v[180:183], v[84:87], v[20:23]
	ds_read_b128 v[172:175], v134 offset:56640
	v_mul_f32_e32 v74, v74, v234
	v_mul_f32_e32 v75, v75, v235
	ds_read_b128 v[220:223], v203 offset:64
	s_waitcnt lgkmcnt(9)
	v_mfma_f32_16x16x32_bf16 v[24:27], v[184:187], v[84:87], v[24:27]
	ds_read_b128 v[176:179], v134 offset:58944
	v_mul_f32_e32 v76, v76, v236
	v_mul_f32_e32 v77, v77, v237
	s_waitcnt lgkmcnt(9)
	v_mfma_f32_16x16x32_bf16 v[28:31], v[188:191], v[84:87], v[28:31]
	ds_read_b128 v[180:183], v134 offset:61248
	v_mul_f32_e32 v78, v78, v238
	v_mul_f32_e32 v79, v79, v239
	s_waitcnt lgkmcnt(9)
	v_mfma_f32_16x16x32_bf16 v[64:67], v[192:195], v[88:91], v[64:67]
	ds_read_b128 v[184:187], v202 offset:27648
	s_waitcnt lgkmcnt(9)
	v_mfma_f32_16x16x32_bf16 v[68:71], v[196:199], v[88:91], v[68:71]
	ds_read_b128 v[188:191], v202 offset:29952
	s_waitcnt lgkmcnt(9)
	v_mfma_f32_16x16x32_bf16 v[72:75], v[160:163], v[88:91], v[72:75]
	ds_read_b128 v[192:195], v202 offset:32256
	s_waitcnt lgkmcnt(9)
	v_mfma_f32_16x16x32_bf16 v[76:79], v[164:167], v[88:91], v[76:79]
	ds_read_b128 v[196:199], v202 offset:34560
	s_waitcnt lgkmcnt(9)
	v_mfma_f32_16x16x32_bf16 v[64:67], v[168:171], v[92:95], v[64:67]
	ds_read_b128 v[160:163], v202 offset:27712
	s_waitcnt lgkmcnt(8)
	v_mfma_f32_16x16x32_bf16 v[68:71], v[172:175], v[92:95], v[68:71]
	ds_read_b128 v[164:167], v202 offset:30016
	s_waitcnt lgkmcnt(7)
	v_mfma_f32_16x16x32_bf16 v[72:75], v[176:179], v[92:95], v[72:75]
	ds_read_b128 v[168:171], v202 offset:32320
	s_waitcnt lgkmcnt(7)
	v_mfma_f32_16x16x32_bf16 v[76:79], v[180:183], v[92:95], v[76:79]
	ds_read_b128 v[172:175], v202 offset:34624
	s_waitcnt lgkmcnt(7)
	v_mfma_f32_16x16x32_bf16 v[48:51], v[184:187], v[216:219], 0
	s_waitcnt lgkmcnt(6)
	v_mfma_f32_16x16x32_bf16 v[52:55], v[188:191], v[216:219], 0
	s_waitcnt lgkmcnt(5)
	v_mfma_f32_16x16x32_bf16 v[56:59], v[192:195], v[216:219], 0
	s_waitcnt lgkmcnt(4)
	v_mfma_f32_16x16x32_bf16 v[60:63], v[196:199], v[216:219], 0
	s_waitcnt lgkmcnt(3)
	v_mfma_f32_16x16x32_bf16 v[48:51], v[160:163], v[220:223], v[48:51]
	s_waitcnt lgkmcnt(2)
	v_mfma_f32_16x16x32_bf16 v[52:55], v[164:167], v[220:223], v[52:55]
	s_waitcnt lgkmcnt(1)
	v_mfma_f32_16x16x32_bf16 v[56:59], v[168:171], v[220:223], v[56:59]
	s_waitcnt lgkmcnt(0)
	v_mfma_f32_16x16x32_bf16 v[60:63], v[172:175], v[220:223], v[60:63]
	s_waitcnt vmcnt(0)
	s_add_u32 s12, s10, 0
	s_cmp_lt_u32 s12, 4
	s_cbranch_scc1 .Lmy_sc_nost5
	v_cvt_pk_bf16_f32 v246, v64, v65
	v_cvt_pk_bf16_f32 v247, v66, v67
	global_store_short v156, v246, s[24:25]
	global_store_short_d16_hi v156, v246, s[24:25] offset:256
	global_store_short v156, v247, s[24:25] offset:512
	global_store_short_d16_hi v156, v247, s[24:25] offset:768
	v_cvt_pk_bf16_f32 v248, v68, v69
	v_cvt_pk_bf16_f32 v249, v70, v71
	global_store_short v157, v248, s[24:25]
	global_store_short_d16_hi v157, v248, s[24:25] offset:256
	global_store_short v157, v249, s[24:25] offset:512
	global_store_short_d16_hi v157, v249, s[24:25] offset:768
	s_nop 0
	v_cvt_pk_bf16_f32 v246, v72, v73
	v_cvt_pk_bf16_f32 v247, v74, v75
	global_store_short v158, v246, s[24:25]
	global_store_short_d16_hi v158, v246, s[24:25] offset:256
	global_store_short v158, v247, s[24:25] offset:512
	global_store_short_d16_hi v158, v247, s[24:25] offset:768
	v_cvt_pk_bf16_f32 v248, v76, v77
	v_cvt_pk_bf16_f32 v249, v78, v79
	global_store_short v159, v248, s[24:25]
	global_store_short_d16_hi v159, v248, s[24:25] offset:256
	global_store_short v159, v249, s[24:25] offset:512
	global_store_short_d16_hi v159, v249, s[24:25] offset:768
.Lmy_sc_nost5:
	s_waitcnt lgkmcnt(0)
	s_branch .Lmy_sc_j4
.Lmy_sc_h4:
	ds_read_b128 v[208:211], v206 offset:35840
	ds_read_b128 v[212:215], v206 offset:35904
	ds_read_b128 v[216:219], v206 offset:38144
	ds_read_b128 v[220:223], v206 offset:38208
	ds_read_b128 v[160:163], v202 offset:18432
	ds_read_b128 v[164:167], v202 offset:20736
	ds_read_b128 v[168:171], v202 offset:23040
	ds_read_b128 v[172:175], v202 offset:25344
	ds_read_b128 v[176:179], v202 offset:18496
	ds_read_b128 v[180:183], v202 offset:20800
	ds_read_b128 v[184:187], v202 offset:23104
	ds_read_b128 v[188:191], v202 offset:25408
	s_waitcnt lgkmcnt(11)
	s_waitcnt lgkmcnt(7)
	v_mfma_f32_16x16x32_bf16 v[0:3], v[208:211], v[160:163], 0
	v_mfma_f32_16x16x32_bf16 v[16:19], v[216:219], v[160:163], 0
	s_waitcnt lgkmcnt(6)
	v_mfma_f32_16x16x32_bf16 v[4:7], v[208:211], v[164:167], 0
	v_mfma_f32_16x16x32_bf16 v[20:23], v[216:219], v[164:167], 0
	s_waitcnt lgkmcnt(5)
	v_mfma_f32_16x16x32_bf16 v[8:11], v[208:211], v[168:171], 0
	v_mfma_f32_16x16x32_bf16 v[24:27], v[216:219], v[168:171], 0
	s_waitcnt lgkmcnt(4)
	v_mfma_f32_16x16x32_bf16 v[12:15], v[208:211], v[172:175], 0
	v_mfma_f32_16x16x32_bf16 v[28:31], v[216:219], v[172:175], 0
	s_waitcnt lgkmcnt(3)
	v_mfma_f32_16x16x32_bf16 v[0:3], v[212:215], v[176:179], v[0:3]
	v_mfma_f32_16x16x32_bf16 v[16:19], v[220:223], v[176:179], v[16:19]
	s_waitcnt lgkmcnt(2)
	v_mfma_f32_16x16x32_bf16 v[4:7], v[212:215], v[180:183], v[4:7]
	v_mfma_f32_16x16x32_bf16 v[20:23], v[220:223], v[180:183], v[20:23]
	s_waitcnt lgkmcnt(1)
	v_mfma_f32_16x16x32_bf16 v[8:11], v[212:215], v[184:187], v[8:11]
	v_mfma_f32_16x16x32_bf16 v[24:27], v[220:223], v[184:187], v[24:27]
	s_waitcnt lgkmcnt(0)
	v_mfma_f32_16x16x32_bf16 v[12:15], v[212:215], v[188:191], v[12:15]
	v_mfma_f32_16x16x32_bf16 v[28:31], v[220:223], v[188:191], v[28:31]
	v_cvt_pk_bf16_f32 v244, -v0, -v1
	v_cvt_pk_bf16_f32 v245, -v2, -v3
	ds_write_b64 v205, v[244:245] offset:0
	v_cvt_pk_bf16_f32 v250, -v16, -v17
	v_cvt_pk_bf16_f32 v251, -v18, -v19
	ds_write_b64 v205, v[250:251] offset:8
	v_cvt_pk_bf16_f32 v244, -v4, -v5
	v_cvt_pk_bf16_f32 v245, -v6, -v7
	ds_write_b64 v205, v[244:245] offset:4352
	v_cvt_pk_bf16_f32 v250, -v20, -v21
	v_cvt_pk_bf16_f32 v251, -v22, -v23
	ds_write_b64 v205, v[250:251] offset:4360
	v_cvt_pk_bf16_f32 v244, -v8, -v9
	v_cvt_pk_bf16_f32 v245, -v10, -v11
	ds_write_b64 v205, v[244:245] offset:8704
	v_cvt_pk_bf16_f32 v250, -v24, -v25
	v_cvt_pk_bf16_f32 v251, -v26, -v27
	ds_write_b64 v205, v[250:251] offset:8712
	v_cvt_pk_bf16_f32 v244, -v12, -v13
	v_cvt_pk_bf16_f32 v245, -v14, -v15
	ds_write_b64 v205, v[244:245] offset:13056
	v_cvt_pk_bf16_f32 v250, -v28, -v29
	v_cvt_pk_bf16_f32 v251, -v30, -v31
	ds_write_b64 v205, v[250:251] offset:13064
	s_waitcnt vmcnt(0)
	s_waitcnt lgkmcnt(0)
; __device__ __forceinline__ unsigned pack2(float a, float b){ f32x2_t v={a,b}; bf16x2_t r=__builtin_convertvector(v,bf16x2_t); return __builtin_bit_cast(unsigned,r); }
; __device__ __forceinline__ bf16x8 packfrag(f32x4 d0, f32x4 d1){ u32x4 t={pack2(d0[0],d0[1]),pack2(d0[2],d0[3]),pack2(d1[0],d1[1]),pack2(d1[2],d1[3])}; return __builtin_bit_cast(bf16x8,t); }
; #define MF(a,b,c) __builtin_amdgcn_mfma_f32_16x16x32_bf16(a,b,c,0,0,0)
; __device__ __forceinline__ void phase_scan(KP kp_){ asm volatile("" : "+s"(kp_)); const Params p=load_params(kp_);
;     ...
;         __syncthreads();
;         FILL(A);
;         __syncthreads();
;       }
;       { const int s=s2+1;
;         if (s+1<132) PREFETCH(A,s+1);
;       f32x4 wacc[4], vn[4];
;       _Pragma("unroll") for (int i=0;i<4;++i){ wacc[i]=f32x4{0.f,0.f,0.f,0.f}; vn[i]=f32x4{0.f,0.f,0.f,0.f}; }
;       _Pragma("unroll") for (int ks=0;ks<2;++ks){ int kb=(ks*32+kg*8)*2;
;         bf16x8 A=lds128(SKT+(wv*16+r)*144+kb);
;         bf16x8 Bv=lds128(SVT+(wv*16+r)*144+kb);
;         _Pragma("unroll") for (int t=0;t<4;++t){
;           wacc[t]=MF(A, lds128(STW+(t*16+r)*144+kb), wacc[t]);
;           vn[t]=MF(lds128(STU+(t*16+r)*144+kb), Bv, vn[t]); } }
;       _Pragma("unroll") for (int t=0;t<4;++t){ uint2 pk2; pk2.x=pack2(-wacc[t][0],-wacc[t][1]); pk2.y=pack2(-wacc[t][2],-wacc[t][3]);
;         *(uint2*)(smem+SWB+(t*16+r)*272+(wv*16+kg*4)*2)=pk2; }
;       __syncthreads();
;       bf16x8 Sf[4];
;       _Pragma("unroll") for (int q=0;q<4;++q) Sf[q]=packfrag(Sacc[2*q],Sacc[2*q+1]);
;       f32x4 oacc[4];
;       _Pragma("unroll") for (int i=0;i<4;++i) oacc[i]=f32x4{0.f,0.f,0.f,0.f};
;       _Pragma("unroll") for (int q=0;q<4;++q){ int kb=(32*q+kg*4)*2;
;         _Pragma("unroll") for (int t=0;t<4;++t){
;           vn[t]=MF(lds64x2(SWB+(t*16+r)*272+kb), Sf[q], vn[t]);
;           oacc[t]=MF(lds64x2(SQ+(t*16+r)*272+kb), Sf[q], oacc[t]); } }
.Lmy_sc_j4:
	s_barrier
	ds_write2_b64 v138, v[96:97], v[98:99] offset1:2
	ds_write2_b64 v139, v[100:101], v[102:103] offset1:2
	ds_write2_b64 v145, v[128:129], v[130:131] offset1:2
	s_cmp_lg_u32 s3, 0
	s_cbranch_scc1 .Lmy_sc_noe6
	v_mul_f32_e32 v240, 0x3fb8aa3b, v132
	v_readlane_b32 s12, v132, s11
	s_nop 0
	v_exp_f32_e32 v240, v240
	s_nop 1
	v_sub_f32_e32 v241, s12, v132
	v_mov_b32_e32 v242, s12
	s_nop 0
	v_mul_f32_e32 v241, 0x3fb8aa3b, v241
	v_mul_f32_e32 v242, 0x3fb8aa3b, v242
	s_nop 0
	v_exp_f32_e32 v241, v241
	v_exp_f32_e32 v242, v242
	s_nop 1
	ds_write_b32 v147, v240 offset:63488
	ds_write_b32 v147, v241 offset:63744
	ds_write_b32 v147, v242 offset:64000
.Lmy_sc_noe6:
	ds_write2_b64 v140, v[104:105], v[106:107] offset1:2
	ds_write2_b64 v141, v[108:109], v[110:111] offset1:2
	ds_write_b128 v146, v[112:115] offset:0
	ds_write2_b64 v144, v[120:121], v[122:123] offset1:2
	ds_write_b128 v146, v[124:127] offset:27648
	s_waitcnt lgkmcnt(0)
	s_mov_b64 s[24:25], s[22:23]
	s_mov_b32 s19, s18
	s_mov_b64 s[20:21], s[14:15]
	s_mov_b64 s[22:23], s[16:17]
	s_barrier
	s_add_u32 s12, s10, 3
	s_min_u32 s12, s12, 0x83
	s_sub_u32 s13, 3, s12
	s_sub_u32 s0, 0x87, s12
	s_cmp_lt_u32 s12, 4
	s_cselect_b32 s13, s13, s0
	s_cselect_b32 s18, 1, 0
	s_cmp_eq_u32 s2, 0
	s_cselect_b32 s12, s12, s13
	s_mul_i32 s13, s12, 0x60000
	s_cmp_eq_u32 s18, 1
	s_cselect_b32 s14, s4, s6
	s_cselect_b32 s15, s5, s7
	s_add_u32 s14, s14, s13
	s_addc_u32 s15, s15, 0
	s_mul_i32 s13, s12, 0x6400
	s_add_u32 s16, s8, s13
	s_addc_u32 s17, s9, 0
	s_mul_i32 s12, s18, 0x3800
	s_add_u32 s12, s12, 0x800
	s_mul_i32 s13, s18, 0x2e000
	s_sub_u32 s13, 0x30000, s13
	s_cmp_eq_u32 s18, 1
	s_cselect_b64 vcc, -1, 0
	s_add_u32 s36, s14, s12
	s_addc_u32 s37, s15, 0
	s_add_u32 s40, s36, s12
	s_addc_u32 s41, s37, 0
	s_add_u32 s38, s36, s13
	s_addc_u32 s39, s37, 0
	s_add_u32 s42, s40, s13
	s_addc_u32 s43, s41, 0
	s_add_u32 s46, s16, 0x2000
	s_addc_u32 s47, s17, 0
	v_cndmask_b32_e32 v151, v149, v148, vcc
	s_cmp_eq_u32 s33, 1
	s_cselect_b32 s40, s42, s40
	s_cselect_b32 s41, s43, s41
	s_mul_i32 s13, s19, 0x2e000
	s_sub_u32 s13, 0x30000, s13
	s_cmp_eq_u32 s19, 1
	s_cselect_b64 vcc, -1, 0
	s_add_u32 s28, s20, s13
	s_addc_u32 s29, s21, 0
	s_add_u32 s30, s22, 0x4000
	s_addc_u32 s31, s23, 0
	s_add_u32 s34, s22, 0x6000
	s_addc_u32 s35, s23, 0
	v_cndmask_b32_e32 v150, v149, v148, vcc
	global_load_dwordx4 v[96:99], v150, s[20:21]
	global_load_dwordx4 v[100:103], v150, s[28:29]
	global_load_dwordx4 v[128:131], v148, s[30:31]
	s_cmp_lg_u32 s3, 0
	s_cbranch_scc1 .Lmy_sc_nog7
	global_load_dword v132, v147, s[34:35]
.Lmy_sc_nog7:
	global_load_dwordx4 v[104:107], v151, s[36:37]
	global_load_dwordx4 v[108:111], v151, s[38:39]
	global_load_dwordx4 v[112:115], v151, s[40:41]
	global_load_dwordx4 v[120:123], v148, s[16:17]
	global_load_dwordx4 v[124:127], v148, s[46:47]
	s_cmp_ge_u32 s3, 4
	s_cbranch_scc1 .Lmy_sc_h8
	ds_read_b32 v152, v137 offset:64000
	ds_read_b128 v[160:163], v201 offset:0
	ds_read_b128 v[164:167], v201 offset:64
	ds_read_b128 v[168:171], v201 offset:128
	ds_read_b128 v[172:175], v201 offset:192
	ds_read_b128 v[176:179], v201 offset:4352
	ds_read_b128 v[180:183], v201 offset:4416
	ds_read_b128 v[184:187], v201 offset:4480
	ds_read_b128 v[188:191], v201 offset:4544
	ds_read_b128 v[224:227], v137 offset:63744
	ds_read_b128 v[228:231], v137 offset:63808
	v_cvt_pk_bf16_f32 v32, v0, v1
	v_cvt_pk_bf16_f32 v33, v2, v3
	v_cvt_pk_bf16_f32 v34, v4, v5
	v_cvt_pk_bf16_f32 v35, v6, v7
	v_cvt_pk_bf16_f32 v36, v8, v9
	v_cvt_pk_bf16_f32 v37, v10, v11
	v_cvt_pk_bf16_f32 v38, v12, v13
	v_cvt_pk_bf16_f32 v39, v14, v15
	v_cvt_pk_bf16_f32 v40, v16, v17
	v_cvt_pk_bf16_f32 v41, v18, v19
	v_cvt_pk_bf16_f32 v42, v20, v21
	v_cvt_pk_bf16_f32 v43, v22, v23
	v_cvt_pk_bf16_f32 v44, v24, v25
	v_cvt_pk_bf16_f32 v45, v26, v27
	v_cvt_pk_bf16_f32 v46, v28, v29
	v_cvt_pk_bf16_f32 v47, v30, v31
	s_waitcnt lgkmcnt(9)
	v_mfma_f32_16x16x32_bf16 v[48:51], v[160:163], v[32:35], v[48:51]
	ds_read_b128 v[192:195], v201 offset:8704
	v_mul_f32_e32 v0, v152, v0
	v_mul_f32_e32 v1, v152, v1
	s_waitcnt lgkmcnt(9)
	v_mfma_f32_16x16x32_bf16 v[48:51], v[164:167], v[36:39], v[48:51]
	ds_read_b128 v[196:199], v201 offset:8768
	v_mul_f32_e32 v2, v152, v2
	v_mul_f32_e32 v3, v152, v3
	s_waitcnt lgkmcnt(9)
	v_mfma_f32_16x16x32_bf16 v[48:51], v[168:171], v[40:43], v[48:51]
	ds_read_b128 v[160:163], v201 offset:8832
	v_mul_f32_e32 v4, v152, v4
	v_mul_f32_e32 v5, v152, v5
	ds_read_b128 v[232:235], v137 offset:63872
	s_waitcnt lgkmcnt(10)
	v_mfma_f32_16x16x32_bf16 v[48:51], v[172:175], v[44:47], v[48:51]
	ds_read_b128 v[164:167], v201 offset:8896
	v_mul_f32_e32 v6, v152, v6
	v_mul_f32_e32 v7, v152, v7
	s_waitcnt lgkmcnt(10)
	v_mfma_f32_16x16x32_bf16 v[52:55], v[176:179], v[32:35], v[52:55]
	ds_read_b128 v[168:171], v201 offset:13056
	v_mul_f32_e32 v8, v152, v8
	v_mul_f32_e32 v9, v152, v9
	ds_read_b128 v[236:239], v137 offset:63936
	s_waitcnt lgkmcnt(11)
	v_mfma_f32_16x16x32_bf16 v[52:55], v[180:183], v[36:39], v[52:55]
	ds_read_b128 v[172:175], v201 offset:13120
	v_mul_f32_e32 v10, v152, v10
	v_mul_f32_e32 v11, v152, v11
	s_waitcnt lgkmcnt(11)
	v_mfma_f32_16x16x32_bf16 v[52:55], v[184:187], v[40:43], v[52:55]
	ds_read_b128 v[176:179], v201 offset:13184
	v_mul_f32_e32 v12, v152, v12
	v_mul_f32_e32 v13, v152, v13
	s_waitcnt lgkmcnt(11)
	v_mfma_f32_16x16x32_bf16 v[52:55], v[188:191], v[44:47], v[52:55]
	ds_read_b128 v[180:183], v201 offset:13248
	v_mul_f32_e32 v14, v152, v14
	v_mul_f32_e32 v15, v152, v15
	s_waitcnt lgkmcnt(9)
	v_mfma_f32_16x16x32_bf16 v[56:59], v[192:195], v[32:35], v[56:59]
	ds_read_b128 v[184:187], v133 offset:0
	v_mul_f32_e32 v16, v152, v16
	v_mul_f32_e32 v17, v152, v17
	s_waitcnt lgkmcnt(9)
; __device__ __forceinline__ bf16x8 packfrag(f32x4 d0, f32x4 d1){ u32x4 t={pack2(d0[0],d0[1]),pack2(d0[2],d0[3]),pack2(d1[0],d1[1]),pack2(d1[2],d1[3])}; return __builtin_bit_cast(bf16x8,t); }
; #define MF(a,b,c) __builtin_amdgcn_mfma_f32_16x16x32_bf16(a,b,c,0,0,0)
; __device__ __forceinline__ void phase_scan(KP kp_){ asm volatile("" : "+s"(kp_)); const Params p=load_params(kp_);
;     ...
;       _Pragma("unroll") for (int q=0;q<4;++q){ int kb=(32*q+kg*4)*2;
;         _Pragma("unroll") for (int t=0;t<4;++t){
;           vn[t]=MF(lds64x2(SWB+(t*16+r)*272+kb), Sf[q], vn[t]);
;           oacc[t]=MF(lds64x2(SQ+(t*16+r)*272+kb), Sf[q], oacc[t]); } }
;       const float* gcs=(const float*)(smem+SGC);
;       float gl = d ? gcs[0] : gcs[63];
;       float gam=__expf(gl);
;       f32x4 vs[4];
;       _Pragma("unroll") for (int t=0;t<4;++t){ float4 g4=*(const float4*)(gcs+t*16+kg*4);
;         oacc[t][0]*=__expf(g4.x); oacc[t][1]*=__expf(g4.y); oacc[t][2]*=__expf(g4.z); oacc[t][3]*=__expf(g4.w);
;         vs[t][0]=vn[t][0]*__expf(gl-g4.x); vs[t][1]=vn[t][1]*__expf(gl-g4.y); vs[t][2]=vn[t][2]*__expf(gl-g4.z); vs[t][3]=vn[t][3]*__expf(gl-g4.w); }
;       bf16x8 Vf[2], Wf[2];
;       _Pragma("unroll") for (int q=0;q<2;++q){ Vf[q]=packfrag(vn[2*q],vn[2*q+1]); Wf[q]=packfrag(vs[2*q],vs[2*q+1]); }
;       _Pragma("unroll") for (int q=0;q<2;++q){ int kb=(32*q+kg*4)*2;
;         _Pragma("unroll") for (int t=0;t<4;++t) oacc[t]=MF(lds64x2(SAT+(t*16+r)*144+kb), Vf[q], oacc[t]); }
;       _Pragma("unroll") for (int m8=0;m8<8;++m8){ Sacc[m8][0]*=gam; Sacc[m8][1]*=gam; Sacc[m8][2]*=gam; Sacc[m8][3]*=gam; }
;       _Pragma("unroll") for (int q=0;q<2;++q){ int kb=(32*q+kg*4)*2;
;         _Pragma("unroll") for (int m8=0;m8<8;++m8) Sacc[m8]=MF(lds64x2(SKT+(m8*16+r)*144+kb), Wf[q], Sacc[m8]); }
	v_mfma_f32_16x16x32_bf16 v[56:59], v[196:199], v[36:39], v[56:59]
	ds_read_b128 v[188:191], v133 offset:64
	v_mul_f32_e32 v18, v152, v18
	v_mul_f32_e32 v19, v152, v19
	s_waitcnt lgkmcnt(9)
	v_mfma_f32_16x16x32_bf16 v[56:59], v[160:163], v[40:43], v[56:59]
	ds_read_b128 v[192:195], v133 offset:128
	v_mul_f32_e32 v20, v152, v20
	v_mul_f32_e32 v21, v152, v21
	s_waitcnt lgkmcnt(8)
	v_mfma_f32_16x16x32_bf16 v[56:59], v[164:167], v[44:47], v[56:59]
	ds_read_b128 v[196:199], v133 offset:192
	v_mul_f32_e32 v22, v152, v22
	v_mul_f32_e32 v23, v152, v23
	s_waitcnt lgkmcnt(8)
	v_mfma_f32_16x16x32_bf16 v[60:63], v[168:171], v[32:35], v[60:63]
	ds_read_b128 v[160:163], v133 offset:4352
	v_mul_f32_e32 v24, v152, v24
	v_mul_f32_e32 v25, v152, v25
	s_waitcnt lgkmcnt(7)
	v_mfma_f32_16x16x32_bf16 v[60:63], v[172:175], v[36:39], v[60:63]
	ds_read_b128 v[164:167], v133 offset:4416
	v_mul_f32_e32 v26, v152, v26
	v_mul_f32_e32 v27, v152, v27
	s_waitcnt lgkmcnt(7)
	v_mfma_f32_16x16x32_bf16 v[60:63], v[176:179], v[40:43], v[60:63]
	ds_read_b128 v[168:171], v133 offset:4480
	v_mul_f32_e32 v28, v152, v28
	v_mul_f32_e32 v29, v152, v29
	s_waitcnt lgkmcnt(7)
	v_mfma_f32_16x16x32_bf16 v[60:63], v[180:183], v[44:47], v[60:63]
	ds_read_b128 v[172:175], v133 offset:4544
	v_mul_f32_e32 v30, v152, v30
	v_mul_f32_e32 v31, v152, v31
	s_waitcnt lgkmcnt(7)
	v_mfma_f32_16x16x32_bf16 v[64:67], v[184:187], v[32:35], 0
	ds_read_b128 v[176:179], v133 offset:8704
	v_mul_f32_e32 v224, v48, v224
	v_mul_f32_e32 v225, v49, v225
	s_waitcnt lgkmcnt(7)
	v_mfma_f32_16x16x32_bf16 v[64:67], v[188:191], v[36:39], v[64:67]
	ds_read_b128 v[180:183], v133 offset:8768
	v_mul_f32_e32 v226, v50, v226
	v_mul_f32_e32 v227, v51, v227
	s_waitcnt lgkmcnt(7)
	v_mfma_f32_16x16x32_bf16 v[64:67], v[192:195], v[40:43], v[64:67]
	ds_read_b128 v[184:187], v133 offset:8832
	v_cvt_pk_bf16_f32 v88, v48, v49
	v_cvt_pk_bf16_f32 v89, v50, v51
	s_waitcnt lgkmcnt(7)
	v_mfma_f32_16x16x32_bf16 v[64:67], v[196:199], v[44:47], v[64:67]
	ds_read_b128 v[188:191], v133 offset:8896
	v_cvt_pk_bf16_f32 v80, v224, v225
	v_cvt_pk_bf16_f32 v81, v226, v227
	s_waitcnt lgkmcnt(7)
	v_mfma_f32_16x16x32_bf16 v[68:71], v[160:163], v[32:35], 0
	ds_read_b128 v[192:195], v133 offset:13056
	v_mul_f32_e32 v228, v52, v228
	v_mul_f32_e32 v229, v53, v229
	s_waitcnt lgkmcnt(7)
	v_mfma_f32_16x16x32_bf16 v[68:71], v[164:167], v[36:39], v[68:71]
	ds_read_b128 v[196:199], v133 offset:13120
	v_mul_f32_e32 v230, v54, v230
	v_mul_f32_e32 v231, v55, v231
	s_waitcnt lgkmcnt(7)
	v_mfma_f32_16x16x32_bf16 v[68:71], v[168:171], v[40:43], v[68:71]
	ds_read_b128 v[160:163], v133 offset:13184
	v_cvt_pk_bf16_f32 v90, v52, v53
	v_cvt_pk_bf16_f32 v91, v54, v55
	s_waitcnt lgkmcnt(7)
	v_mfma_f32_16x16x32_bf16 v[68:71], v[172:175], v[44:47], v[68:71]
	ds_read_b128 v[164:167], v133 offset:13248
	v_cvt_pk_bf16_f32 v82, v228, v229
	v_cvt_pk_bf16_f32 v83, v230, v231
	s_waitcnt lgkmcnt(7)
	v_mfma_f32_16x16x32_bf16 v[72:75], v[176:179], v[32:35], 0
	ds_read_b128 v[168:171], v134 offset:35840
	v_mul_f32_e32 v232, v56, v232
	v_mul_f32_e32 v233, v57, v233
	s_waitcnt lgkmcnt(7)
	v_mfma_f32_16x16x32_bf16 v[72:75], v[180:183], v[36:39], v[72:75]
	ds_read_b128 v[172:175], v134 offset:38144
	v_mul_f32_e32 v234, v58, v234
	v_mul_f32_e32 v235, v59, v235
	s_waitcnt lgkmcnt(7)
	v_mfma_f32_16x16x32_bf16 v[72:75], v[184:187], v[40:43], v[72:75]
	ds_read_b128 v[176:179], v134 offset:40448
	v_cvt_pk_bf16_f32 v92, v56, v57
	v_cvt_pk_bf16_f32 v93, v58, v59
	s_waitcnt lgkmcnt(7)
	v_mfma_f32_16x16x32_bf16 v[72:75], v[188:191], v[44:47], v[72:75]
	ds_read_b128 v[180:183], v134 offset:42752
	v_cvt_pk_bf16_f32 v84, v232, v233
	v_cvt_pk_bf16_f32 v85, v234, v235
	s_waitcnt lgkmcnt(7)
	v_mfma_f32_16x16x32_bf16 v[76:79], v[192:195], v[32:35], 0
	ds_read_b128 v[184:187], v134 offset:45056
	v_mul_f32_e32 v236, v60, v236
	v_mul_f32_e32 v237, v61, v237
	s_waitcnt lgkmcnt(7)
	v_mfma_f32_16x16x32_bf16 v[76:79], v[196:199], v[36:39], v[76:79]
	ds_read_b128 v[188:191], v134 offset:47360
	v_mul_f32_e32 v238, v62, v238
	v_mul_f32_e32 v239, v63, v239
	s_waitcnt lgkmcnt(7)
	v_mfma_f32_16x16x32_bf16 v[76:79], v[160:163], v[40:43], v[76:79]
	ds_read_b128 v[192:195], v134 offset:49664
	v_cvt_pk_bf16_f32 v94, v60, v61
	v_cvt_pk_bf16_f32 v95, v62, v63
	s_waitcnt lgkmcnt(7)
	v_mfma_f32_16x16x32_bf16 v[76:79], v[164:167], v[44:47], v[76:79]
	ds_read_b128 v[196:199], v134 offset:51968
	v_cvt_pk_bf16_f32 v86, v236, v237
	v_cvt_pk_bf16_f32 v87, v238, v239
	s_waitcnt lgkmcnt(7)
	v_mfma_f32_16x16x32_bf16 v[0:3], v[168:171], v[80:83], v[0:3]
	ds_read_b128 v[160:163], v134 offset:35904
	ds_read_b128 v[224:227], v137 offset:63488
	s_waitcnt lgkmcnt(8)
	v_mfma_f32_16x16x32_bf16 v[4:7], v[172:175], v[80:83], v[4:7]
	ds_read_b128 v[164:167], v134 offset:38208
	ds_read_b128 v[228:231], v137 offset:63552
	s_waitcnt lgkmcnt(9)
	v_mfma_f32_16x16x32_bf16 v[8:11], v[176:179], v[80:83], v[8:11]
	ds_read_b128 v[168:171], v134 offset:40512
	ds_read_b128 v[232:235], v137 offset:63616
	s_waitcnt lgkmcnt(10)
	v_mfma_f32_16x16x32_bf16 v[12:15], v[180:183], v[80:83], v[12:15]
	ds_read_b128 v[172:175], v134 offset:42816
	ds_read_b128 v[236:239], v137 offset:63680
	s_waitcnt lgkmcnt(11)
; __device__ __forceinline__ bf16x8 packfrag(f32x4 d0, f32x4 d1){ u32x4 t={pack2(d0[0],d0[1]),pack2(d0[2],d0[3]),pack2(d1[0],d1[1]),pack2(d1[2],d1[3])}; return __builtin_bit_cast(bf16x8,t); }
; #define MF(a,b,c) __builtin_amdgcn_mfma_f32_16x16x32_bf16(a,b,c,0,0,0)
; __device__ __forceinline__ void phase_scan(KP kp_){ asm volatile("" : "+s"(kp_)); const Params p=load_params(kp_);
;     ...
;       _Pragma("unroll") for (int t=0;t<4;++t){ float4 g4=*(const float4*)(gcs+t*16+kg*4);
;         oacc[t][0]*=__expf(g4.x); oacc[t][1]*=__expf(g4.y); oacc[t][2]*=__expf(g4.z); oacc[t][3]*=__expf(g4.w);
;         vs[t][0]=vn[t][0]*__expf(gl-g4.x); vs[t][1]=vn[t][1]*__expf(gl-g4.y); vs[t][2]=vn[t][2]*__expf(gl-g4.z); vs[t][3]=vn[t][3]*__expf(gl-g4.w); }
;       bf16x8 Vf[2], Wf[2];
;       _Pragma("unroll") for (int q=0;q<2;++q){ Vf[q]=packfrag(vn[2*q],vn[2*q+1]); Wf[q]=packfrag(vs[2*q],vs[2*q+1]); }
;       _Pragma("unroll") for (int q=0;q<2;++q){ int kb=(32*q+kg*4)*2;
;         _Pragma("unroll") for (int t=0;t<4;++t) oacc[t]=MF(lds64x2(SAT+(t*16+r)*144+kb), Vf[q], oacc[t]); }
;       _Pragma("unroll") for (int m8=0;m8<8;++m8){ Sacc[m8][0]*=gam; Sacc[m8][1]*=gam; Sacc[m8][2]*=gam; Sacc[m8][3]*=gam; }
;       _Pragma("unroll") for (int q=0;q<2;++q){ int kb=(32*q+kg*4)*2;
;         _Pragma("unroll") for (int m8=0;m8<8;++m8) Sacc[m8]=MF(lds64x2(SKT+(m8*16+r)*144+kb), Wf[q], Sacc[m8]); }
;       if (s>=4){ int cidx=4+(d?131-s:s-4); char* op=tabase+(size_t)((b*8+h)*132+cidx)*TA_STRIDE;
;         _Pragma("unroll") for (int t=0;t<4;++t) _Pragma("unroll") for (int j=0;j<4;++j)
;           *(u16*)(op+((t*16+kg*4+j)*128+wv*16+r)*2)=f2bf(oacc[t][j]); }
;     ...
;       _Pragma("unroll") for (int ks=0;ks<2;++ks){ int kb=(ks*32+kg*8)*2;
;         bf16x8 A=lds128(SKT+(wv*16+r)*144+kb);
;         bf16x8 Bv=lds128(SVT+(wv*16+r)*144+kb);
;         _Pragma("unroll") for (int t=0;t<4;++t){
;           wacc[t]=MF(A, lds128(STW+(t*16+r)*144+kb), wacc[t]);
;           vn[t]=MF(lds128(STU+(t*16+r)*144+kb), Bv, vn[t]); } }
	v_mfma_f32_16x16x32_bf16 v[16:19], v[184:187], v[80:83], v[16:19]
	ds_read_b128 v[176:179], v134 offset:45120
	s_waitcnt lgkmcnt(11)
	v_mfma_f32_16x16x32_bf16 v[20:23], v[188:191], v[80:83], v[20:23]
	ds_read_b128 v[180:183], v134 offset:47424
	s_waitcnt lgkmcnt(11)
	v_mfma_f32_16x16x32_bf16 v[24:27], v[192:195], v[80:83], v[24:27]
	ds_read_b128 v[184:187], v134 offset:49728
	s_waitcnt lgkmcnt(11)
	v_mfma_f32_16x16x32_bf16 v[28:31], v[196:199], v[80:83], v[28:31]
	ds_read_b128 v[188:191], v134 offset:52032
	s_waitcnt lgkmcnt(11)
	v_mfma_f32_16x16x32_bf16 v[0:3], v[160:163], v[84:87], v[0:3]
	ds_read_b128 v[192:195], v134 offset:54272
	s_waitcnt lgkmcnt(11)
	v_mul_f32_e32 v64, v64, v224
	v_mul_f32_e32 v65, v65, v225
	s_waitcnt lgkmcnt(10)
	v_mfma_f32_16x16x32_bf16 v[4:7], v[164:167], v[84:87], v[4:7]
	ds_read_b128 v[196:199], v134 offset:56576
	v_mul_f32_e32 v66, v66, v226
	v_mul_f32_e32 v67, v67, v227
	s_waitcnt lgkmcnt(9)
	v_mfma_f32_16x16x32_bf16 v[8:11], v[168:171], v[84:87], v[8:11]
	ds_read_b128 v[160:163], v134 offset:58880
	v_mul_f32_e32 v68, v68, v228
	v_mul_f32_e32 v69, v69, v229
	s_waitcnt lgkmcnt(8)
	v_mfma_f32_16x16x32_bf16 v[12:15], v[172:175], v[84:87], v[12:15]
	ds_read_b128 v[164:167], v134 offset:61184
	v_mul_f32_e32 v70, v70, v230
	v_mul_f32_e32 v71, v71, v231
	s_waitcnt lgkmcnt(7)
	v_mfma_f32_16x16x32_bf16 v[16:19], v[176:179], v[84:87], v[16:19]
	ds_read_b128 v[168:171], v134 offset:54336
	v_mul_f32_e32 v72, v72, v232
	v_mul_f32_e32 v73, v73, v233
	ds_read_b128 v[216:219], v203 offset:0
	s_waitcnt lgkmcnt(8)
	v_mfma_f32_16x16x32_bf16 v[20:23], v[180:183], v[84:87], v[20:23]
	ds_read_b128 v[172:175], v134 offset:56640
	v_mul_f32_e32 v74, v74, v234
	v_mul_f32_e32 v75, v75, v235
	ds_read_b128 v[220:223], v203 offset:64
	s_waitcnt lgkmcnt(9)
	v_mfma_f32_16x16x32_bf16 v[24:27], v[184:187], v[84:87], v[24:27]
	ds_read_b128 v[176:179], v134 offset:58944
	v_mul_f32_e32 v76, v76, v236
	v_mul_f32_e32 v77, v77, v237
	s_waitcnt lgkmcnt(9)
	v_mfma_f32_16x16x32_bf16 v[28:31], v[188:191], v[84:87], v[28:31]
	ds_read_b128 v[180:183], v134 offset:61248
	v_mul_f32_e32 v78, v78, v238
	v_mul_f32_e32 v79, v79, v239
	s_waitcnt lgkmcnt(9)
	v_mfma_f32_16x16x32_bf16 v[64:67], v[192:195], v[88:91], v[64:67]
	ds_read_b128 v[184:187], v202 offset:27648
	s_waitcnt lgkmcnt(9)
	v_mfma_f32_16x16x32_bf16 v[68:71], v[196:199], v[88:91], v[68:71]
	ds_read_b128 v[188:191], v202 offset:29952
	s_waitcnt lgkmcnt(9)
	v_mfma_f32_16x16x32_bf16 v[72:75], v[160:163], v[88:91], v[72:75]
	ds_read_b128 v[192:195], v202 offset:32256
	s_waitcnt lgkmcnt(9)
	v_mfma_f32_16x16x32_bf16 v[76:79], v[164:167], v[88:91], v[76:79]
	ds_read_b128 v[196:199], v202 offset:34560
	s_waitcnt lgkmcnt(9)
	v_mfma_f32_16x16x32_bf16 v[64:67], v[168:171], v[92:95], v[64:67]
	ds_read_b128 v[160:163], v202 offset:27712
	s_waitcnt lgkmcnt(8)
	v_mfma_f32_16x16x32_bf16 v[68:71], v[172:175], v[92:95], v[68:71]
	ds_read_b128 v[164:167], v202 offset:30016
	s_waitcnt lgkmcnt(7)
	v_mfma_f32_16x16x32_bf16 v[72:75], v[176:179], v[92:95], v[72:75]
	ds_read_b128 v[168:171], v202 offset:32320
	s_waitcnt lgkmcnt(7)
	v_mfma_f32_16x16x32_bf16 v[76:79], v[180:183], v[92:95], v[76:79]
	ds_read_b128 v[172:175], v202 offset:34624
	s_waitcnt lgkmcnt(7)
	v_mfma_f32_16x16x32_bf16 v[48:51], v[184:187], v[216:219], 0
	s_waitcnt lgkmcnt(6)
	v_mfma_f32_16x16x32_bf16 v[52:55], v[188:191], v[216:219], 0
	s_waitcnt lgkmcnt(5)
	v_mfma_f32_16x16x32_bf16 v[56:59], v[192:195], v[216:219], 0
	s_waitcnt lgkmcnt(4)
	v_mfma_f32_16x16x32_bf16 v[60:63], v[196:199], v[216:219], 0
	s_waitcnt lgkmcnt(3)
	v_mfma_f32_16x16x32_bf16 v[48:51], v[160:163], v[220:223], v[48:51]
	s_waitcnt lgkmcnt(2)
	v_mfma_f32_16x16x32_bf16 v[52:55], v[164:167], v[220:223], v[52:55]
	s_waitcnt lgkmcnt(1)
	v_mfma_f32_16x16x32_bf16 v[56:59], v[168:171], v[220:223], v[56:59]
	s_waitcnt lgkmcnt(0)
	v_mfma_f32_16x16x32_bf16 v[60:63], v[172:175], v[220:223], v[60:63]
	s_waitcnt vmcnt(0)
	s_add_u32 s12, s10, 1
	s_cmp_lt_u32 s12, 4
	s_cbranch_scc1 .Lmy_sc_nost9
	v_cvt_pk_bf16_f32 v246, v64, v65
	v_cvt_pk_bf16_f32 v247, v66, v67
	global_store_short v156, v246, s[24:25]
	global_store_short_d16_hi v156, v246, s[24:25] offset:256
	global_store_short v156, v247, s[24:25] offset:512
	global_store_short_d16_hi v156, v247, s[24:25] offset:768
	v_cvt_pk_bf16_f32 v248, v68, v69
	v_cvt_pk_bf16_f32 v249, v70, v71
	global_store_short v157, v248, s[24:25]
	global_store_short_d16_hi v157, v248, s[24:25] offset:256
	global_store_short v157, v249, s[24:25] offset:512
	global_store_short_d16_hi v157, v249, s[24:25] offset:768
	s_nop 0
	v_cvt_pk_bf16_f32 v246, v72, v73
	v_cvt_pk_bf16_f32 v247, v74, v75
	global_store_short v158, v246, s[24:25]
	global_store_short_d16_hi v158, v246, s[24:25] offset:256
	global_store_short v158, v247, s[24:25] offset:512
	global_store_short_d16_hi v158, v247, s[24:25] offset:768
	v_cvt_pk_bf16_f32 v248, v76, v77
	v_cvt_pk_bf16_f32 v249, v78, v79
	global_store_short v159, v248, s[24:25]
	global_store_short_d16_hi v159, v248, s[24:25] offset:256
	global_store_short v159, v249, s[24:25] offset:512
	global_store_short_d16_hi v159, v249, s[24:25] offset:768

; __device__ __forceinline__ unsigned pack2(float a, float b){ f32x2_t v={a,b}; bf16x2_t r=__builtin_convertvector(v,bf16x2_t); return __builtin_bit_cast(unsigned,r); }
; #define MF(a,b,c) __builtin_amdgcn_mfma_f32_16x16x32_bf16(a,b,c,0,0,0)
; __device__ __forceinline__ void phase_scan(KP kp_){ asm volatile("" : "+s"(kp_)); const Params p=load_params(kp_);
;     ...
;       _Pragma("unroll") for (int ks=0;ks<2;++ks){ int kb=(ks*32+kg*8)*2;
;         bf16x8 A=lds128(SKT+(wv*16+r)*144+kb);
;         bf16x8 Bv=lds128(SVT+(wv*16+r)*144+kb);
;         _Pragma("unroll") for (int t=0;t<4;++t){
;           wacc[t]=MF(A, lds128(STW+(t*16+r)*144+kb), wacc[t]);
;           vn[t]=MF(lds128(STU+(t*16+r)*144+kb), Bv, vn[t]); } }
;       _Pragma("unroll") for (int t=0;t<4;++t){ uint2 pk2; pk2.x=pack2(-wacc[t][0],-wacc[t][1]); pk2.y=pack2(-wacc[t][2],-wacc[t][3]);
;         *(uint2*)(smem+SWB+(t*16+r)*272+(wv*16+kg*4)*2)=pk2; }
.Lmy_sc_h8:
	ds_read_b128 v[208:211], v206 offset:17408
	ds_read_b128 v[212:215], v206 offset:17472
	ds_read_b128 v[216:219], v206 offset:19712
	ds_read_b128 v[220:223], v206 offset:19776
	ds_read_b128 v[160:163], v202 offset:18432
	ds_read_b128 v[164:167], v202 offset:20736
	ds_read_b128 v[168:171], v202 offset:23040
	ds_read_b128 v[172:175], v202 offset:25344
	ds_read_b128 v[176:179], v202 offset:18496
	ds_read_b128 v[180:183], v202 offset:20800
	ds_read_b128 v[184:187], v202 offset:23104
	ds_read_b128 v[188:191], v202 offset:25408
	s_waitcnt lgkmcnt(11)
	s_waitcnt lgkmcnt(7)
	v_mfma_f32_16x16x32_bf16 v[0:3], v[208:211], v[160:163], 0
	v_mfma_f32_16x16x32_bf16 v[16:19], v[216:219], v[160:163], 0
	s_waitcnt lgkmcnt(6)
	v_mfma_f32_16x16x32_bf16 v[4:7], v[208:211], v[164:167], 0
	v_mfma_f32_16x16x32_bf16 v[20:23], v[216:219], v[164:167], 0
	s_waitcnt lgkmcnt(5)
	v_mfma_f32_16x16x32_bf16 v[8:11], v[208:211], v[168:171], 0
	v_mfma_f32_16x16x32_bf16 v[24:27], v[216:219], v[168:171], 0
	s_waitcnt lgkmcnt(4)
	v_mfma_f32_16x16x32_bf16 v[12:15], v[208:211], v[172:175], 0
	v_mfma_f32_16x16x32_bf16 v[28:31], v[216:219], v[172:175], 0
	s_waitcnt lgkmcnt(3)
	v_mfma_f32_16x16x32_bf16 v[0:3], v[212:215], v[176:179], v[0:3]
	v_mfma_f32_16x16x32_bf16 v[16:19], v[220:223], v[176:179], v[16:19]
	s_waitcnt lgkmcnt(2)
	v_mfma_f32_16x16x32_bf16 v[4:7], v[212:215], v[180:183], v[4:7]
	v_mfma_f32_16x16x32_bf16 v[20:23], v[220:223], v[180:183], v[20:23]
	s_waitcnt lgkmcnt(1)
	v_mfma_f32_16x16x32_bf16 v[8:11], v[212:215], v[184:187], v[8:11]
	v_mfma_f32_16x16x32_bf16 v[24:27], v[220:223], v[184:187], v[24:27]
	s_waitcnt lgkmcnt(0)
	v_mfma_f32_16x16x32_bf16 v[12:15], v[212:215], v[188:191], v[12:15]
	v_mfma_f32_16x16x32_bf16 v[28:31], v[220:223], v[188:191], v[28:31]
	v_cvt_pk_bf16_f32 v244, -v0, -v1
	v_cvt_pk_bf16_f32 v245, -v2, -v3
	ds_write_b64 v204, v[244:245] offset:0
	v_cvt_pk_bf16_f32 v250, -v16, -v17
	v_cvt_pk_bf16_f32 v251, -v18, -v19
	ds_write_b64 v204, v[250:251] offset:8
	v_cvt_pk_bf16_f32 v244, -v4, -v5
	v_cvt_pk_bf16_f32 v245, -v6, -v7
	ds_write_b64 v204, v[244:245] offset:4352
	v_cvt_pk_bf16_f32 v250, -v20, -v21
	v_cvt_pk_bf16_f32 v251, -v22, -v23
	ds_write_b64 v204, v[250:251] offset:4360
	v_cvt_pk_bf16_f32 v244, -v8, -v9
	v_cvt_pk_bf16_f32 v245, -v10, -v11
	ds_write_b64 v204, v[244:245] offset:8704
	v_cvt_pk_bf16_f32 v250, -v24, -v25
	v_cvt_pk_bf16_f32 v251, -v26, -v27
	ds_write_b64 v204, v[250:251] offset:8712
	v_cvt_pk_bf16_f32 v244, -v12, -v13
	v_cvt_pk_bf16_f32 v245, -v14, -v15
	ds_write_b64 v204, v[244:245] offset:13056
	v_cvt_pk_bf16_f32 v250, -v28, -v29
	v_cvt_pk_bf16_f32 v251, -v30, -v31
	ds_write_b64 v204, v[250:251] offset:13064
	s_waitcnt vmcnt(0)
	s_waitcnt lgkmcnt(0)

; __device__ __forceinline__ void phase_scan(KP kp_){ asm volatile("" : "+s"(kp_)); const Params p=load_params(kp_);
;     ...
;         __syncthreads();
;         if (s+1<132) FILL(A);
;         __syncthreads();
;       }
;     }
.Lmy_sc_noe10:
	ds_write2_b64 v142, v[104:105], v[106:107] offset1:2
	ds_write2_b64 v143, v[108:109], v[110:111] offset1:2
	ds_write_b128 v146, v[112:115] offset:0
	ds_write2_b64 v144, v[120:121], v[122:123] offset1:2
	ds_write_b128 v146, v[124:127] offset:27648
	s_waitcnt lgkmcnt(0)
	s_mov_b64 s[24:25], s[22:23]
	s_mov_b32 s19, s18
	s_mov_b64 s[20:21], s[14:15]
	s_mov_b64 s[22:23], s[16:17]
	s_barrier
	s_add_u32 s10, s10, 2
	s_cmp_lt_u32 s10, 0x84
	s_cbranch_scc1 .Lmy_scan_loop

; __global__ void __launch_bounds__(NTH) mega(Params p_arg){
	.amdhsa_kernel _Z4mega6Params
		.amdhsa_group_segment_fixed_size 0
		.amdhsa_private_segment_fixed_size 0
		.amdhsa_kernarg_size 496
		.amdhsa_user_sgpr_count 2
		.amdhsa_user_sgpr_dispatch_ptr 0
		.amdhsa_user_sgpr_queue_ptr 0
		.amdhsa_user_sgpr_kernarg_segment_ptr 1
		.amdhsa_user_sgpr_dispatch_id 0
		.amdhsa_user_sgpr_kernarg_preload_length 0
		.amdhsa_user_sgpr_kernarg_preload_offset 0
		.amdhsa_user_sgpr_private_segment_size 0
		.amdhsa_uses_dynamic_stack 0
		.amdhsa_enable_private_segment 0
		.amdhsa_system_sgpr_workgroup_id_x 1
		.amdhsa_system_sgpr_workgroup_id_y 0
		.amdhsa_system_sgpr_workgroup_id_z 0
		.amdhsa_system_sgpr_workgroup_info 0
		.amdhsa_system_vgpr_workitem_id 2
		.amdhsa_next_free_vgpr 255
		.amdhsa_next_free_sgpr 100
		.amdhsa_accum_offset 256
		.amdhsa_reserve_vcc 1
		.amdhsa_float_round_mode_32 0
		.amdhsa_float_round_mode_16_64 0
		.amdhsa_float_denorm_mode_32 3
		.amdhsa_float_denorm_mode_16_64 3
		.amdhsa_dx10_clamp 1
		.amdhsa_ieee_mode 1
		.amdhsa_fp16_overflow 0
		.amdhsa_tg_split 0
		.amdhsa_exception_fp_ieee_invalid_op 0
		.amdhsa_exception_fp_denorm_src 0
		.amdhsa_exception_fp_ieee_div_zero 0
		.amdhsa_exception_fp_ieee_overflow 0
		.amdhsa_exception_fp_ieee_underflow 0
		.amdhsa_exception_fp_ieee_inexact 0
		.amdhsa_exception_int_div_zero 0
	.end_amdhsa_kernel

; __global__ void __launch_bounds__(NTH) mega(Params p_arg){
amdhsa.kernels:
  - .agpr_count:     0
    .args:
      - .offset:         0
        .size:           240
        .value_kind:     by_value
      - .offset:         240
        .size:           4
        .value_kind:     hidden_block_count_x
      - .offset:         244
        .size:           4
        .value_kind:     hidden_block_count_y
      - .offset:         248
        .size:           4
        .value_kind:     hidden_block_count_z
      - .offset:         252
        .size:           2
        .value_kind:     hidden_group_size_x
      - .offset:         254
        .size:           2
        .value_kind:     hidden_group_size_y
      - .offset:         256
        .size:           2
        .value_kind:     hidden_group_size_z
      - .offset:         258
        .size:           2
        .value_kind:     hidden_remainder_x
      - .offset:         260
        .size:           2
        .value_kind:     hidden_remainder_y
      - .offset:         262
        .size:           2
        .value_kind:     hidden_remainder_z
      - .offset:         280
        .size:           8
        .value_kind:     hidden_global_offset_x
      - .offset:         288
        .size:           8
        .value_kind:     hidden_global_offset_y
      - .offset:         296
        .size:           8
        .value_kind:     hidden_global_offset_z
      - .offset:         304
        .size:           2
        .value_kind:     hidden_grid_dims
      - .offset:         328
        .size:           8
        .value_kind:     hidden_multigrid_sync_arg
      - .offset:         360
        .size:           4
        .value_kind:     hidden_dynamic_lds_size
    .group_segment_fixed_size: 0
    .kernarg_segment_align: 8
    .kernarg_segment_size: 496
    .language:       OpenCL C
    .language_version:
      - 2
      - 0
    .max_flat_workgroup_size: 512
    .name:           _Z4mega6Params
    .private_segment_fixed_size: 0
    .sgpr_count:     106
    .sgpr_spill_count: 197
    .symbol:         _Z4mega6Params.kd
    .uniform_work_group_size: 1
    .uses_dynamic_stack: false
    .vgpr_count:     255
    .vgpr_spill_count: 0
    .wavefront_size: 64
